# v99 + GEMM1 epilogue stores (PROJ/XB/ZB) system-scope write-through (sc0 sc1) instead of agent-scope (sc1)
# baseline (speedup 1.0000x reference)
; __device__ __forceinline__ unsigned cvt_pk_bf16(float lo, float hi) { const f32x2_t v = {lo, hi}; return __builtin_bit_cast(unsigned, __builtin_convertvector(v, bf16x2_t)); }
; __device__ __forceinline__ float silu_f(float x) { return x * __builtin_amdgcn_rcpf(1.0f + __expf(-x)); }
;     __device__ __forceinline__ void operator()(const f32x4 (&acc)[2][2][4][2], const Unit& u, int wr, int wc, int fr, int fq) const {
;         const int row0 = u.pm * BM + wr * 64 + fr, lc = wc * 32 + 8 * fq;
;         const int pnl = (f8tiles && u.pn >= 12) ? u.pn + 4 : u.pn;
;         const int type = (pnl < 8) ? 0 : (pnl < 12) ? 1 : (pnl < 16) ? 3 : 4;
; #pragma unroll
;         for (int ai = 0; ai < 2; ++ai)
; #pragma unroll
;             for (int m = 0; m < 4; ++m) { const int row = row0 + ai * HALF + m * 16;
;                 if (type == 0) { f32x4 p0, p1;
; #pragma unroll
;                     for (int j = 0; j < 4; ++j) { p0[j] = (acc[ai][0][m][0][j] * osc) * silu_f(acc[ai][1][m][0][j] * osc); p1[j] = (acc[ai][0][m][1][j] * osc) * silu_f(acc[ai][1][m][1][j] * osc); }
;                     u32x4 w; w.x = cvt_pk_bf16(p0[0], p0[1]); w.y = cvt_pk_bf16(p0[2], p0[3]); w.z = cvt_pk_bf16(p1[0], p1[1]); w.w = cvt_pk_bf16(p1[2], p1[3]);
;                     *(u32x4*)(P + (size_t)row * 5120 + pnl * HALF + lc) = w; }
.LBB0_400:
	s_cmp_lt_i32 s44, 8
	s_cselect_b64 s[8:9], -1, 0
	s_cmp_lt_u32 s44, 16
	v_lshl_add_u32 v136, s2, 8, v131
	s_cselect_b32 s2, 3, 4
	s_cmp_lt_u32 s44, 12
	s_cselect_b64 s[76:77], -1, 0
	s_and_b64 s[4:5], s[76:77], exec
	s_cselect_b32 s2, 1, s2
	s_cmp_gt_i32 s44, 7
	s_cselect_b64 s[4:5], -1, 0
	s_and_b64 vcc, s[4:5], exec
	s_cselect_b32 s2, s2, 0
	s_lshl_b32 s86, s44, 7
	s_ashr_i32 s87, s86, 31
	s_cmp_eq_u32 s2, 4
	s_cselect_b64 s[4:5], -1, 0
	s_and_b32 s6, s44, 0x7ffffffc
	s_cmp_lg_u32 s6, 8
	s_cselect_b64 s[84:85], -1, 0
	s_cmp_eq_u32 s2, 3
	s_cselect_b64 s[78:79], -1, 0
	s_and_b64 s[6:7], s[78:79], exec
	s_cselect_b32 s2, -12, -16
	s_mov_b64 s[6:7], -1
	v_lshlrev_b32_e32 v172, 1, v130
	s_cbranch_vccnz .LBB0_402
	v_pk_mul_f32 v[138:139], v[134:135], v[118:119]
	v_pk_mul_f32 v[144:145], v[134:135], v[126:127]
	v_mul_f32_e32 v137, 0xbfb8aa3b, v138
	v_exp_f32_e32 v137, v137
	v_pk_mul_f32 v[146:147], v[134:135], v[122:123]
	v_pk_mul_f32 v[148:149], v[134:135], v[128:129]
	v_pk_mul_f32 v[150:151], v[134:135], v[124:125]
	v_add_f32_e32 v137, 1.0, v137
	v_rcp_f32_e32 v140, v137
	v_mul_f32_e32 v137, 0xbfb8aa3b, v139
	v_exp_f32_e32 v137, v137
	s_nop 0
	v_add_f32_e32 v137, 1.0, v137
	v_rcp_f32_e32 v141, v137
	s_nop 0
	v_pk_mul_f32 v[138:139], v[138:139], v[140:141]
	v_pk_mul_f32 v[140:141], v[134:135], v[114:115]
	v_pk_mul_f32 v[138:139], v[138:139], v[144:145]
	v_mul_f32_e32 v137, 0xbfb8aa3b, v140
	v_exp_f32_e32 v137, v137
	v_cvt_pk_bf16_f32 v138, v138, v139
	v_add_f32_e32 v137, 1.0, v137
	v_rcp_f32_e32 v144, v137
	v_mul_f32_e32 v137, 0xbfb8aa3b, v141
	v_exp_f32_e32 v137, v137
	s_nop 0
	v_add_f32_e32 v137, 1.0, v137
	v_rcp_f32_e32 v145, v137
	s_nop 0
	v_pk_mul_f32 v[140:141], v[140:141], v[144:145]
	v_pk_mul_f32 v[144:145], v[134:135], v[120:121]
	v_pk_mul_f32 v[140:141], v[140:141], v[146:147]
	v_mul_f32_e32 v137, 0xbfb8aa3b, v144
	v_exp_f32_e32 v137, v137
	v_cvt_pk_bf16_f32 v140, v140, v141
	v_add_f32_e32 v137, 1.0, v137
	v_rcp_f32_e32 v146, v137
	v_mul_f32_e32 v137, 0xbfb8aa3b, v145
	v_exp_f32_e32 v137, v137
	s_nop 0
	v_add_f32_e32 v137, 1.0, v137
	v_rcp_f32_e32 v147, v137
	s_nop 0
	v_pk_mul_f32 v[144:145], v[144:145], v[146:147]
	v_pk_mul_f32 v[146:147], v[134:135], v[116:117]
	v_pk_mul_f32 v[144:145], v[144:145], v[148:149]
	v_mul_f32_e32 v137, 0xbfb8aa3b, v146
	v_exp_f32_e32 v137, v137
	v_cvt_pk_bf16_f32 v139, v144, v145
	v_mov_b64_e32 v[144:145], s[14:15]
	v_mad_i64_i32 v[144:145], s[6:7], v136, s40, v[144:145]
	v_add_f32_e32 v137, 1.0, v137
	v_rcp_f32_e32 v148, v137
	v_mul_f32_e32 v137, 0xbfb8aa3b, v147
	v_exp_f32_e32 v137, v137
	v_lshl_add_u64 v[144:145], s[86:87], 1, v[144:145]
	v_lshl_add_u64 v[144:145], v[144:145], 0, v[172:173]
	s_mov_b64 s[6:7], 0
	v_add_f32_e32 v137, 1.0, v137
	v_rcp_f32_e32 v149, v137
	s_nop 0
	v_pk_mul_f32 v[146:147], v[146:147], v[148:149]
	s_nop 0
	v_pk_mul_f32 v[146:147], v[146:147], v[150:151]
	s_nop 0
	v_cvt_pk_bf16_f32 v141, v146, v147
	global_store_dwordx4 v[144:145], v[138:141], off sc0 sc1

; __device__ __forceinline__ unsigned cvt_pk_bf16(float lo, float hi) { const f32x2_t v = {lo, hi}; return __builtin_bit_cast(unsigned, __builtin_convertvector(v, bf16x2_t)); }
;     __device__ __forceinline__ void operator()(const f32x4 (&acc)[2][2][4][2], const Unit& u, int wr, int wc, int fr, int fq) const {
;     ...
;                         u32x4 w; w.x = cvt_pk_bf16(v0[0], v0[1]); w.y = cvt_pk_bf16(v0[2], v0[3]); w.z = cvt_pk_bf16(v1[0], v1[1]); w.w = cvt_pk_bf16(v1[2], v1[3]);
;                         if (type == 1) *(u32x4*)(P + (size_t)row * 5120 + 1024 + (pnl - 8) * BM + bj * HALF + lc) = w;
;                         else { const int cg = (pnl - (type == 3 ? 12 : 16)) * BM + bj * HALF + lc;
;                             *(u32x4*)((type == 3 ? XB : ZB) + ((size_t)(cg >> 4) * 8448 + row) * 16 + (cg & 8)) = w; } }
.LBB0_410:
	v_ashrrev_i32_e32 v137, 31, v136
	v_cvt_pk_bf16_f32 v122, v138, v139
	v_cvt_pk_bf16_f32 v123, v128, v129
	v_cvt_pk_bf16_f32 v124, v124, v125
	v_cvt_pk_bf16_f32 v125, v140, v141
	s_mov_b64 s[88:89], -1
	s_and_b64 vcc, exec, s[84:85]
	s_cbranch_vccz .LBB0_412
	v_ashrrev_i32_e32 v128, 4, v144
	s_and_b64 s[44:45], s[78:79], exec
	v_mad_i64_i32 v[128:129], s[88:89], v128, s41, v[136:137]
	s_cselect_b32 s45, s29, s53
	s_cselect_b32 s44, s28, s52
	v_lshlrev_b64 v[128:129], 5, v[128:129]
	v_lshl_add_u64 v[128:129], s[44:45], 0, v[128:129]
	v_lshlrev_b32_e32 v138, 1, v174
	v_mov_b32_e32 v139, v173
	v_lshl_add_u64 v[128:129], v[128:129], 0, v[138:139]
	global_store_dwordx4 v[128:129], v[122:125], off sc0 sc1
	s_mov_b64 s[88:89], 0
.LBB0_412:
	v_mad_i64_i32 v[128:129], s[44:45], v136, s40, 0
	s_andn2_b64 vcc, exec, s[88:89]
	v_lshl_add_u64 v[128:129], s[14:15], 0, v[128:129]
	s_cbranch_vccnz .LBB0_414
	s_lshl_b32 s34, s67, 1
	v_lshl_add_u64 v[138:139], v[128:129], 0, s[34:35]
	v_lshl_add_u64 v[138:139], v[138:139], 0, v[172:173]
	global_store_dwordx4 v[138:139], v[122:125], off offset:-2048 sc0 sc1

; __device__ __forceinline__ unsigned cvt_pk_bf16(float lo, float hi) { const f32x2_t v = {lo, hi}; return __builtin_bit_cast(unsigned, __builtin_convertvector(v, bf16x2_t)); }
;     __device__ __forceinline__ void operator()(const f32x4 (&acc)[2][2][4][2], const Unit& u, int wr, int wc, int fr, int fq) const {
;     ...
;                         u32x4 w; w.x = cvt_pk_bf16(v0[0], v0[1]); w.y = cvt_pk_bf16(v0[2], v0[3]); w.z = cvt_pk_bf16(v1[0], v1[1]); w.w = cvt_pk_bf16(v1[2], v1[3]);
;                         if (type == 1) *(u32x4*)(P + (size_t)row * 5120 + 1024 + (pnl - 8) * BM + bj * HALF + lc) = w;
;                         else { const int cg = (pnl - (type == 3 ? 12 : 16)) * BM + bj * HALF + lc;
;                             *(u32x4*)((type == 3 ? XB : ZB) + ((size_t)(cg >> 4) * 8448 + row) * 16 + (cg & 8)) = w; } }
.LBB0_418:
	v_cvt_pk_bf16_f32 v114, v118, v119
	v_cvt_pk_bf16_f32 v115, v120, v121
	v_cvt_pk_bf16_f32 v116, v116, v117
	v_cvt_pk_bf16_f32 v117, v122, v123
	s_and_b64 vcc, exec, s[6:7]
	s_mov_b64 s[6:7], -1
	s_cbranch_vccnz .LBB0_423
	v_ashrrev_i32_e32 v118, 4, v144
	v_or_b32_e32 v118, 8, v118
	s_and_b64 s[6:7], s[78:79], exec
	v_mad_i64_i32 v[118:119], s[44:45], v118, s41, v[136:137]
	s_cselect_b32 s7, s29, s53
	s_cselect_b32 s6, s28, s52
	v_lshlrev_b64 v[118:119], 5, v[118:119]
	v_lshl_add_u64 v[118:119], s[6:7], 0, v[118:119]
	v_lshlrev_b32_e32 v120, 1, v174
	v_mov_b32_e32 v121, v173
	v_lshl_add_u64 v[118:119], v[118:119], 0, v[120:121]
	global_store_dwordx4 v[118:119], v[114:117], off sc0 sc1
	s_cbranch_execz .LBB0_424

; __device__ __forceinline__ unsigned cvt_pk_bf16(float lo, float hi) { const f32x2_t v = {lo, hi}; return __builtin_bit_cast(unsigned, __builtin_convertvector(v, bf16x2_t)); }
;     __device__ __forceinline__ void operator()(const f32x4 (&acc)[2][2][4][2], const Unit& u, int wr, int wc, int fr, int fq) const {
;     ...
;                         u32x4 w; w.x = cvt_pk_bf16(v0[0], v0[1]); w.y = cvt_pk_bf16(v0[2], v0[3]); w.z = cvt_pk_bf16(v1[0], v1[1]); w.w = cvt_pk_bf16(v1[2], v1[3]);
;                         if (type == 1) *(u32x4*)(P + (size_t)row * 5120 + 1024 + (pnl - 8) * BM + bj * HALF + lc) = w;
.LBB0_424:
	s_lshl_b32 s34, s67, 1
	v_lshl_add_u64 v[118:119], v[128:129], 0, s[34:35]
	v_lshl_add_u64 v[118:119], v[118:119], 0, v[172:173]
	global_store_dwordx4 v[118:119], v[114:117], off offset:-1792 sc0 sc1
	s_andn2_b64 vcc, exec, s[76:77]
	s_cbranch_vccnz .LBB0_428

; __device__ __forceinline__ unsigned cvt_pk_bf16(float lo, float hi) { const f32x2_t v = {lo, hi}; return __builtin_bit_cast(unsigned, __builtin_convertvector(v, bf16x2_t)); }
; __device__ __forceinline__ float silu_f(float x) { return x * __builtin_amdgcn_rcpf(1.0f + __expf(-x)); }
;     __device__ __forceinline__ void operator()(const f32x4 (&acc)[2][2][4][2], const Unit& u, int wr, int wc, int fr, int fq) const {
;     ...
;             for (int m = 0; m < 4; ++m) { const int row = row0 + ai * HALF + m * 16;
;                 if (type == 0) { f32x4 p0, p1;
; #pragma unroll
;                     for (int j = 0; j < 4; ++j) { p0[j] = (acc[ai][0][m][0][j] * osc) * silu_f(acc[ai][1][m][0][j] * osc); p1[j] = (acc[ai][0][m][1][j] * osc) * silu_f(acc[ai][1][m][1][j] * osc); }
;                     u32x4 w; w.x = cvt_pk_bf16(p0[0], p0[1]); w.y = cvt_pk_bf16(p0[2], p0[3]); w.z = cvt_pk_bf16(p1[0], p1[1]); w.w = cvt_pk_bf16(p1[2], p1[3]);
;                     *(u32x4*)(P + (size_t)row * 5120 + pnl * HALF + lc) = w; }
.LBB0_428:
	s_waitcnt lgkmcnt(0)
	v_cndmask_b32_e64 v115, 0, 1, s[8:9]
	v_or_b32_e32 v114, 16, v136
	v_cmp_ne_u32_e64 s[6:7], 1, v115
	s_andn2_b64 vcc, exec, s[8:9]
	s_mov_b64 s[8:9], -1
	s_cbranch_vccnz .LBB0_430
	v_pk_mul_f32 v[116:117], v[134:135], v[102:103]
	v_pk_mul_f32 v[120:121], v[134:135], v[110:111]
	v_mul_f32_e32 v115, 0xbfb8aa3b, v116
	v_exp_f32_e32 v115, v115
	v_pk_mul_f32 v[122:123], v[134:135], v[106:107]
	v_pk_mul_f32 v[124:125], v[134:135], v[112:113]
	v_pk_mul_f32 v[126:127], v[134:135], v[108:109]
	v_add_f32_e32 v115, 1.0, v115
	v_rcp_f32_e32 v118, v115
	v_mul_f32_e32 v115, 0xbfb8aa3b, v117
	v_exp_f32_e32 v115, v115
	s_nop 0
	v_add_f32_e32 v115, 1.0, v115
	v_rcp_f32_e32 v119, v115
	s_nop 0
	v_pk_mul_f32 v[116:117], v[116:117], v[118:119]
	v_pk_mul_f32 v[118:119], v[134:135], v[98:99]
	v_pk_mul_f32 v[116:117], v[116:117], v[120:121]
	v_mul_f32_e32 v115, 0xbfb8aa3b, v118
	v_exp_f32_e32 v115, v115
	v_cvt_pk_bf16_f32 v116, v116, v117
	v_add_f32_e32 v115, 1.0, v115
	v_rcp_f32_e32 v120, v115
	v_mul_f32_e32 v115, 0xbfb8aa3b, v119
	v_exp_f32_e32 v115, v115
	s_nop 0
	v_add_f32_e32 v115, 1.0, v115
	v_rcp_f32_e32 v121, v115
	s_nop 0
	v_pk_mul_f32 v[118:119], v[118:119], v[120:121]
	v_pk_mul_f32 v[120:121], v[134:135], v[104:105]
	v_pk_mul_f32 v[118:119], v[118:119], v[122:123]
	v_mul_f32_e32 v115, 0xbfb8aa3b, v120
	v_exp_f32_e32 v115, v115
	v_cvt_pk_bf16_f32 v118, v118, v119
	v_add_f32_e32 v115, 1.0, v115
	v_rcp_f32_e32 v122, v115
	v_mul_f32_e32 v115, 0xbfb8aa3b, v121
	v_exp_f32_e32 v115, v115
	s_nop 0
	v_add_f32_e32 v115, 1.0, v115
	v_rcp_f32_e32 v123, v115
	s_nop 0
	v_pk_mul_f32 v[120:121], v[120:121], v[122:123]
	v_pk_mul_f32 v[122:123], v[134:135], v[100:101]
	v_pk_mul_f32 v[120:121], v[120:121], v[124:125]
	v_mul_f32_e32 v115, 0xbfb8aa3b, v122
	v_exp_f32_e32 v115, v115
	v_cvt_pk_bf16_f32 v117, v120, v121
	v_mov_b64_e32 v[120:121], s[14:15]
	v_mad_i64_i32 v[120:121], s[8:9], v114, s40, v[120:121]
	v_add_f32_e32 v115, 1.0, v115
	v_rcp_f32_e32 v124, v115
	v_mul_f32_e32 v115, 0xbfb8aa3b, v123
	v_exp_f32_e32 v115, v115
	v_lshl_add_u64 v[120:121], s[86:87], 1, v[120:121]
	v_lshl_add_u64 v[120:121], v[120:121], 0, v[172:173]
	s_mov_b64 s[8:9], 0
	v_add_f32_e32 v115, 1.0, v115
	v_rcp_f32_e32 v125, v115
	s_nop 0
	v_pk_mul_f32 v[122:123], v[122:123], v[124:125]
	s_nop 0
	v_pk_mul_f32 v[122:123], v[122:123], v[126:127]
	s_nop 0
	v_cvt_pk_bf16_f32 v119, v122, v123
	global_store_dwordx4 v[120:121], v[116:119], off sc0 sc1

; __device__ __forceinline__ unsigned cvt_pk_bf16(float lo, float hi) { const f32x2_t v = {lo, hi}; return __builtin_bit_cast(unsigned, __builtin_convertvector(v, bf16x2_t)); }
;     __device__ __forceinline__ void operator()(const f32x4 (&acc)[2][2][4][2], const Unit& u, int wr, int wc, int fr, int fq) const {
;     ...
;                         u32x4 w; w.x = cvt_pk_bf16(v0[0], v0[1]); w.y = cvt_pk_bf16(v0[2], v0[3]); w.z = cvt_pk_bf16(v1[0], v1[1]); w.w = cvt_pk_bf16(v1[2], v1[3]);
;                         if (type == 1) *(u32x4*)(P + (size_t)row * 5120 + 1024 + (pnl - 8) * BM + bj * HALF + lc) = w;
;                         else { const int cg = (pnl - (type == 3 ? 12 : 16)) * BM + bj * HALF + lc;
;                             *(u32x4*)((type == 3 ? XB : ZB) + ((size_t)(cg >> 4) * 8448 + row) * 16 + (cg & 8)) = w; } }
.LBB0_438:
	v_ashrrev_i32_e32 v115, 31, v114
	v_cvt_pk_bf16_f32 v106, v116, v117
	v_cvt_pk_bf16_f32 v107, v112, v113
	v_cvt_pk_bf16_f32 v108, v108, v109
	v_cvt_pk_bf16_f32 v109, v118, v119
	s_and_b64 vcc, exec, s[8:9]
	s_mov_b64 s[88:89], -1
	s_cbranch_vccnz .LBB0_440
	v_ashrrev_i32_e32 v112, 4, v144
	s_and_b64 s[44:45], s[78:79], exec
	v_mad_i64_i32 v[112:113], s[88:89], v112, s41, v[114:115]
	s_cselect_b32 s45, s29, s53
	s_cselect_b32 s44, s28, s52
	v_lshlrev_b64 v[112:113], 5, v[112:113]
	v_lshl_add_u64 v[112:113], s[44:45], 0, v[112:113]
	v_lshlrev_b32_e32 v116, 1, v174
	v_mov_b32_e32 v117, v173
	v_lshl_add_u64 v[112:113], v[112:113], 0, v[116:117]
	s_mov_b64 s[88:89], 0
	global_store_dwordx4 v[112:113], v[106:109], off sc0 sc1
.LBB0_440:
	v_mad_i64_i32 v[112:113], s[44:45], v114, s40, 0
	s_andn2_b64 vcc, exec, s[88:89]
	v_lshl_add_u64 v[112:113], s[14:15], 0, v[112:113]
	s_cbranch_vccnz .LBB0_442
	s_lshl_b32 s34, s67, 1
	v_lshl_add_u64 v[116:117], v[112:113], 0, s[34:35]
	v_lshl_add_u64 v[116:117], v[116:117], 0, v[172:173]
	global_store_dwordx4 v[116:117], v[106:109], off offset:-2048 sc0 sc1

; __device__ __forceinline__ unsigned cvt_pk_bf16(float lo, float hi) { const f32x2_t v = {lo, hi}; return __builtin_bit_cast(unsigned, __builtin_convertvector(v, bf16x2_t)); }
;     __device__ __forceinline__ void operator()(const f32x4 (&acc)[2][2][4][2], const Unit& u, int wr, int wc, int fr, int fq) const {
;     ...
;                         u32x4 w; w.x = cvt_pk_bf16(v0[0], v0[1]); w.y = cvt_pk_bf16(v0[2], v0[3]); w.z = cvt_pk_bf16(v1[0], v1[1]); w.w = cvt_pk_bf16(v1[2], v1[3]);
;                         if (type == 1) *(u32x4*)(P + (size_t)row * 5120 + 1024 + (pnl - 8) * BM + bj * HALF + lc) = w;
;                         else { const int cg = (pnl - (type == 3 ? 12 : 16)) * BM + bj * HALF + lc;
;                             *(u32x4*)((type == 3 ? XB : ZB) + ((size_t)(cg >> 4) * 8448 + row) * 16 + (cg & 8)) = w; } }
.LBB0_446:
	v_cvt_pk_bf16_f32 v98, v102, v103
	v_cvt_pk_bf16_f32 v99, v104, v105
	v_cvt_pk_bf16_f32 v100, v100, v101
	v_cvt_pk_bf16_f32 v101, v106, v107
	s_and_b64 vcc, exec, s[8:9]
	s_mov_b64 s[8:9], -1
	s_cbranch_vccnz .LBB0_454
	v_ashrrev_i32_e32 v102, 4, v144
	v_or_b32_e32 v102, 8, v102
	s_and_b64 s[8:9], s[78:79], exec
	v_mad_i64_i32 v[102:103], s[44:45], v102, s41, v[114:115]
	s_cselect_b32 s9, s29, s53
	s_cselect_b32 s8, s28, s52
	v_lshlrev_b64 v[102:103], 5, v[102:103]
	v_lshl_add_u64 v[102:103], s[8:9], 0, v[102:103]
	v_lshlrev_b32_e32 v104, 1, v174
	v_mov_b32_e32 v105, v173
	v_lshl_add_u64 v[102:103], v[102:103], 0, v[104:105]
	global_store_dwordx4 v[102:103], v[98:101], off sc0 sc1
	s_cbranch_execz .LBB0_455

; __device__ __forceinline__ unsigned cvt_pk_bf16(float lo, float hi) { const f32x2_t v = {lo, hi}; return __builtin_bit_cast(unsigned, __builtin_convertvector(v, bf16x2_t)); }
;     __device__ __forceinline__ void operator()(const f32x4 (&acc)[2][2][4][2], const Unit& u, int wr, int wc, int fr, int fq) const {
;     ...
;                         u32x4 w; w.x = cvt_pk_bf16(v0[0], v0[1]); w.y = cvt_pk_bf16(v0[2], v0[3]); w.z = cvt_pk_bf16(v1[0], v1[1]); w.w = cvt_pk_bf16(v1[2], v1[3]);
;                         if (type == 1) *(u32x4*)(P + (size_t)row * 5120 + 1024 + (pnl - 8) * BM + bj * HALF + lc) = w;
.LBB0_455:
	s_lshl_b32 s34, s67, 1
	v_lshl_add_u64 v[102:103], v[112:113], 0, s[34:35]
	v_lshl_add_u64 v[102:103], v[102:103], 0, v[172:173]
	global_store_dwordx4 v[102:103], v[98:101], off offset:-1792 sc0 sc1
	s_andn2_b64 vcc, exec, s[76:77]
	s_cbranch_vccz .LBB0_449

; __device__ __forceinline__ unsigned cvt_pk_bf16(float lo, float hi) { const f32x2_t v = {lo, hi}; return __builtin_bit_cast(unsigned, __builtin_convertvector(v, bf16x2_t)); }
; __device__ __forceinline__ float silu_f(float x) { return x * __builtin_amdgcn_rcpf(1.0f + __expf(-x)); }
;     __device__ __forceinline__ void operator()(const f32x4 (&acc)[2][2][4][2], const Unit& u, int wr, int wc, int fr, int fq) const {
;     ...
;             for (int m = 0; m < 4; ++m) { const int row = row0 + ai * HALF + m * 16;
;                 if (type == 0) { f32x4 p0, p1;
; #pragma unroll
;                     for (int j = 0; j < 4; ++j) { p0[j] = (acc[ai][0][m][0][j] * osc) * silu_f(acc[ai][1][m][0][j] * osc); p1[j] = (acc[ai][0][m][1][j] * osc) * silu_f(acc[ai][1][m][1][j] * osc); }
;                     u32x4 w; w.x = cvt_pk_bf16(p0[0], p0[1]); w.y = cvt_pk_bf16(p0[2], p0[3]); w.z = cvt_pk_bf16(p1[0], p1[1]); w.w = cvt_pk_bf16(p1[2], p1[3]);
;                     *(u32x4*)(P + (size_t)row * 5120 + pnl * HALF + lc) = w; }
.LBB0_457:
	s_waitcnt lgkmcnt(0)
	v_pk_mul_f32 v[100:101], v[134:135], v[86:87]
	v_pk_mul_f32 v[104:105], v[134:135], v[94:95]
	v_mul_f32_e32 v99, 0xbfb8aa3b, v100
	v_exp_f32_e32 v99, v99
	v_pk_mul_f32 v[106:107], v[134:135], v[90:91]
	v_pk_mul_f32 v[108:109], v[134:135], v[96:97]
	v_pk_mul_f32 v[110:111], v[134:135], v[92:93]
	v_add_f32_e32 v99, 1.0, v99
	v_rcp_f32_e32 v102, v99
	v_mul_f32_e32 v99, 0xbfb8aa3b, v101
	v_exp_f32_e32 v99, v99
	s_nop 0
	v_add_f32_e32 v99, 1.0, v99
	v_rcp_f32_e32 v103, v99
	s_nop 0
	v_pk_mul_f32 v[100:101], v[100:101], v[102:103]
	v_pk_mul_f32 v[102:103], v[134:135], v[82:83]
	v_pk_mul_f32 v[100:101], v[100:101], v[104:105]
	v_mul_f32_e32 v99, 0xbfb8aa3b, v102
	v_exp_f32_e32 v99, v99
	v_cvt_pk_bf16_f32 v100, v100, v101
	v_add_f32_e32 v99, 1.0, v99
	v_rcp_f32_e32 v104, v99
	v_mul_f32_e32 v99, 0xbfb8aa3b, v103
	v_exp_f32_e32 v99, v99
	s_nop 0
	v_add_f32_e32 v99, 1.0, v99
	v_rcp_f32_e32 v105, v99
	s_nop 0
	v_pk_mul_f32 v[102:103], v[102:103], v[104:105]
	v_pk_mul_f32 v[104:105], v[134:135], v[88:89]
	v_pk_mul_f32 v[102:103], v[102:103], v[106:107]
	v_mul_f32_e32 v99, 0xbfb8aa3b, v104
	v_exp_f32_e32 v99, v99
	v_cvt_pk_bf16_f32 v102, v102, v103
	v_add_f32_e32 v99, 1.0, v99
	v_rcp_f32_e32 v106, v99
	v_mul_f32_e32 v99, 0xbfb8aa3b, v105
	v_exp_f32_e32 v99, v99
	s_nop 0
	v_add_f32_e32 v99, 1.0, v99
	v_rcp_f32_e32 v107, v99
	s_nop 0
	v_pk_mul_f32 v[104:105], v[104:105], v[106:107]
	v_pk_mul_f32 v[106:107], v[134:135], v[84:85]
	v_pk_mul_f32 v[104:105], v[104:105], v[108:109]
	v_mul_f32_e32 v99, 0xbfb8aa3b, v106
	v_exp_f32_e32 v99, v99
	v_cvt_pk_bf16_f32 v101, v104, v105
	v_mov_b64_e32 v[104:105], s[14:15]
	v_mad_i64_i32 v[104:105], s[8:9], v98, s40, v[104:105]
	v_add_f32_e32 v99, 1.0, v99
	v_rcp_f32_e32 v108, v99
	v_mul_f32_e32 v99, 0xbfb8aa3b, v107
	v_exp_f32_e32 v99, v99
	v_lshl_add_u64 v[104:105], s[86:87], 1, v[104:105]
	v_lshl_add_u64 v[104:105], v[104:105], 0, v[172:173]
	s_mov_b64 s[8:9], 0
	v_add_f32_e32 v99, 1.0, v99
	v_rcp_f32_e32 v109, v99
	s_nop 0
	v_pk_mul_f32 v[106:107], v[106:107], v[108:109]
	s_nop 0
	v_pk_mul_f32 v[106:107], v[106:107], v[110:111]
	s_nop 0
	v_cvt_pk_bf16_f32 v103, v106, v107
	global_store_dwordx4 v[104:105], v[100:103], off sc0 sc1

; __device__ __forceinline__ unsigned cvt_pk_bf16(float lo, float hi) { const f32x2_t v = {lo, hi}; return __builtin_bit_cast(unsigned, __builtin_convertvector(v, bf16x2_t)); }
;     __device__ __forceinline__ void operator()(const f32x4 (&acc)[2][2][4][2], const Unit& u, int wr, int wc, int fr, int fq) const {
;     ...
;                         u32x4 w; w.x = cvt_pk_bf16(v0[0], v0[1]); w.y = cvt_pk_bf16(v0[2], v0[3]); w.z = cvt_pk_bf16(v1[0], v1[1]); w.w = cvt_pk_bf16(v1[2], v1[3]);
;                         if (type == 1) *(u32x4*)(P + (size_t)row * 5120 + 1024 + (pnl - 8) * BM + bj * HALF + lc) = w;
;                         else { const int cg = (pnl - (type == 3 ? 12 : 16)) * BM + bj * HALF + lc;
;                             *(u32x4*)((type == 3 ? XB : ZB) + ((size_t)(cg >> 4) * 8448 + row) * 16 + (cg & 8)) = w; } }
.LBB0_466:
	v_ashrrev_i32_e32 v99, 31, v98
	v_cvt_pk_bf16_f32 v90, v100, v101
	v_cvt_pk_bf16_f32 v91, v96, v97
	v_cvt_pk_bf16_f32 v92, v92, v93
	v_cvt_pk_bf16_f32 v93, v102, v103
	s_and_b64 vcc, exec, s[8:9]
	s_mov_b64 s[88:89], -1
	s_cbranch_vccnz .LBB0_468
	v_ashrrev_i32_e32 v96, 4, v144
	s_and_b64 s[44:45], s[78:79], exec
	v_mad_i64_i32 v[96:97], s[88:89], v96, s41, v[98:99]
	s_cselect_b32 s45, s29, s53
	s_cselect_b32 s44, s28, s52
	v_lshlrev_b64 v[96:97], 5, v[96:97]
	v_lshl_add_u64 v[96:97], s[44:45], 0, v[96:97]
	v_lshlrev_b32_e32 v100, 1, v174
	v_mov_b32_e32 v101, v173
	v_lshl_add_u64 v[96:97], v[96:97], 0, v[100:101]
	s_mov_b64 s[88:89], 0
	global_store_dwordx4 v[96:97], v[90:93], off sc0 sc1
.LBB0_468:
	v_mad_i64_i32 v[96:97], s[44:45], v98, s40, 0
	s_andn2_b64 vcc, exec, s[88:89]
	v_lshl_add_u64 v[96:97], s[14:15], 0, v[96:97]
	s_cbranch_vccnz .LBB0_470
	s_lshl_b32 s34, s67, 1
	v_lshl_add_u64 v[100:101], v[96:97], 0, s[34:35]
	v_lshl_add_u64 v[100:101], v[100:101], 0, v[172:173]
	global_store_dwordx4 v[100:101], v[90:93], off offset:-2048 sc0 sc1

; __device__ __forceinline__ unsigned cvt_pk_bf16(float lo, float hi) { const f32x2_t v = {lo, hi}; return __builtin_bit_cast(unsigned, __builtin_convertvector(v, bf16x2_t)); }
;     __device__ __forceinline__ void operator()(const f32x4 (&acc)[2][2][4][2], const Unit& u, int wr, int wc, int fr, int fq) const {
;     ...
;                         u32x4 w; w.x = cvt_pk_bf16(v0[0], v0[1]); w.y = cvt_pk_bf16(v0[2], v0[3]); w.z = cvt_pk_bf16(v1[0], v1[1]); w.w = cvt_pk_bf16(v1[2], v1[3]);
;                         if (type == 1) *(u32x4*)(P + (size_t)row * 5120 + 1024 + (pnl - 8) * BM + bj * HALF + lc) = w;
;                         else { const int cg = (pnl - (type == 3 ? 12 : 16)) * BM + bj * HALF + lc;
;                             *(u32x4*)((type == 3 ? XB : ZB) + ((size_t)(cg >> 4) * 8448 + row) * 16 + (cg & 8)) = w; } }
.LBB0_474:
	v_cvt_pk_bf16_f32 v82, v86, v87
	v_cvt_pk_bf16_f32 v83, v88, v89
	v_cvt_pk_bf16_f32 v84, v84, v85
	v_cvt_pk_bf16_f32 v85, v90, v91
	s_and_b64 vcc, exec, s[8:9]
	s_mov_b64 s[8:9], -1
	s_cbranch_vccnz .LBB0_482
	v_ashrrev_i32_e32 v86, 4, v144
	v_or_b32_e32 v86, 8, v86
	s_and_b64 s[8:9], s[78:79], exec
	v_mad_i64_i32 v[86:87], s[44:45], v86, s41, v[98:99]
	s_cselect_b32 s9, s29, s53
	s_cselect_b32 s8, s28, s52
	v_lshlrev_b64 v[86:87], 5, v[86:87]
	v_lshl_add_u64 v[86:87], s[8:9], 0, v[86:87]
	v_lshlrev_b32_e32 v88, 1, v174
	v_mov_b32_e32 v89, v173
	v_lshl_add_u64 v[86:87], v[86:87], 0, v[88:89]
	global_store_dwordx4 v[86:87], v[82:85], off sc0 sc1
	s_cbranch_execz .LBB0_483

; __device__ __forceinline__ unsigned cvt_pk_bf16(float lo, float hi) { const f32x2_t v = {lo, hi}; return __builtin_bit_cast(unsigned, __builtin_convertvector(v, bf16x2_t)); }
;     __device__ __forceinline__ void operator()(const f32x4 (&acc)[2][2][4][2], const Unit& u, int wr, int wc, int fr, int fq) const {
;     ...
;                         u32x4 w; w.x = cvt_pk_bf16(v0[0], v0[1]); w.y = cvt_pk_bf16(v0[2], v0[3]); w.z = cvt_pk_bf16(v1[0], v1[1]); w.w = cvt_pk_bf16(v1[2], v1[3]);
;                         if (type == 1) *(u32x4*)(P + (size_t)row * 5120 + 1024 + (pnl - 8) * BM + bj * HALF + lc) = w;
.LBB0_483:
	s_lshl_b32 s34, s67, 1
	v_lshl_add_u64 v[86:87], v[96:97], 0, s[34:35]
	v_lshl_add_u64 v[86:87], v[86:87], 0, v[172:173]
	global_store_dwordx4 v[86:87], v[82:85], off offset:-1792 sc0 sc1
	s_andn2_b64 vcc, exec, s[76:77]
	s_cbranch_vccz .LBB0_477

; __device__ __forceinline__ unsigned cvt_pk_bf16(float lo, float hi) { const f32x2_t v = {lo, hi}; return __builtin_bit_cast(unsigned, __builtin_convertvector(v, bf16x2_t)); }
; __device__ __forceinline__ float silu_f(float x) { return x * __builtin_amdgcn_rcpf(1.0f + __expf(-x)); }
;     __device__ __forceinline__ void operator()(const f32x4 (&acc)[2][2][4][2], const Unit& u, int wr, int wc, int fr, int fq) const {
;     ...
;             for (int m = 0; m < 4; ++m) { const int row = row0 + ai * HALF + m * 16;
;                 if (type == 0) { f32x4 p0, p1;
; #pragma unroll
;                     for (int j = 0; j < 4; ++j) { p0[j] = (acc[ai][0][m][0][j] * osc) * silu_f(acc[ai][1][m][0][j] * osc); p1[j] = (acc[ai][0][m][1][j] * osc) * silu_f(acc[ai][1][m][1][j] * osc); }
;                     u32x4 w; w.x = cvt_pk_bf16(p0[0], p0[1]); w.y = cvt_pk_bf16(p0[2], p0[3]); w.z = cvt_pk_bf16(p1[0], p1[1]); w.w = cvt_pk_bf16(p1[2], p1[3]);
;                     *(u32x4*)(P + (size_t)row * 5120 + pnl * HALF + lc) = w; }
.LBB0_485:
	s_waitcnt lgkmcnt(0)
	v_pk_mul_f32 v[84:85], v[134:135], v[70:71]
	v_pk_mul_f32 v[88:89], v[134:135], v[78:79]
	v_mul_f32_e32 v83, 0xbfb8aa3b, v84
	v_exp_f32_e32 v83, v83
	v_pk_mul_f32 v[90:91], v[134:135], v[74:75]
	v_pk_mul_f32 v[92:93], v[134:135], v[80:81]
	v_pk_mul_f32 v[94:95], v[134:135], v[76:77]
	v_add_f32_e32 v83, 1.0, v83
	v_rcp_f32_e32 v86, v83
	v_mul_f32_e32 v83, 0xbfb8aa3b, v85
	v_exp_f32_e32 v83, v83
	s_nop 0
	v_add_f32_e32 v83, 1.0, v83
	v_rcp_f32_e32 v87, v83
	s_nop 0
	v_pk_mul_f32 v[84:85], v[84:85], v[86:87]
	v_pk_mul_f32 v[86:87], v[134:135], v[66:67]
	v_pk_mul_f32 v[84:85], v[84:85], v[88:89]
	v_mul_f32_e32 v83, 0xbfb8aa3b, v86
	v_exp_f32_e32 v83, v83
	v_cvt_pk_bf16_f32 v84, v84, v85
	v_add_f32_e32 v83, 1.0, v83
	v_rcp_f32_e32 v88, v83
	v_mul_f32_e32 v83, 0xbfb8aa3b, v87
	v_exp_f32_e32 v83, v83
	s_nop 0
	v_add_f32_e32 v83, 1.0, v83
	v_rcp_f32_e32 v89, v83
	s_nop 0
	v_pk_mul_f32 v[86:87], v[86:87], v[88:89]
	v_pk_mul_f32 v[88:89], v[134:135], v[72:73]
	v_pk_mul_f32 v[86:87], v[86:87], v[90:91]
	v_mul_f32_e32 v83, 0xbfb8aa3b, v88
	v_exp_f32_e32 v83, v83
	v_cvt_pk_bf16_f32 v86, v86, v87
	v_add_f32_e32 v83, 1.0, v83
	v_rcp_f32_e32 v90, v83
	v_mul_f32_e32 v83, 0xbfb8aa3b, v89
	v_exp_f32_e32 v83, v83
	s_nop 0
	v_add_f32_e32 v83, 1.0, v83
	v_rcp_f32_e32 v91, v83
	s_nop 0
	v_pk_mul_f32 v[88:89], v[88:89], v[90:91]
	v_pk_mul_f32 v[90:91], v[134:135], v[68:69]
	v_pk_mul_f32 v[88:89], v[88:89], v[92:93]
	v_mul_f32_e32 v83, 0xbfb8aa3b, v90
	v_exp_f32_e32 v83, v83
	v_cvt_pk_bf16_f32 v85, v88, v89
	v_mov_b64_e32 v[88:89], s[14:15]
	v_mad_i64_i32 v[88:89], s[8:9], v82, s40, v[88:89]
	v_add_f32_e32 v83, 1.0, v83
	v_rcp_f32_e32 v92, v83
	v_mul_f32_e32 v83, 0xbfb8aa3b, v91
	v_exp_f32_e32 v83, v83
	v_lshl_add_u64 v[88:89], s[86:87], 1, v[88:89]
	v_lshl_add_u64 v[88:89], v[88:89], 0, v[172:173]
	s_mov_b64 s[8:9], 0
	v_add_f32_e32 v83, 1.0, v83
	v_rcp_f32_e32 v93, v83
	s_nop 0
	v_pk_mul_f32 v[90:91], v[90:91], v[92:93]
	s_nop 0
	v_pk_mul_f32 v[90:91], v[90:91], v[94:95]
	s_nop 0
	v_cvt_pk_bf16_f32 v87, v90, v91
	global_store_dwordx4 v[88:89], v[84:87], off sc0 sc1

; __device__ __forceinline__ unsigned cvt_pk_bf16(float lo, float hi) { const f32x2_t v = {lo, hi}; return __builtin_bit_cast(unsigned, __builtin_convertvector(v, bf16x2_t)); }
;     __device__ __forceinline__ void operator()(const f32x4 (&acc)[2][2][4][2], const Unit& u, int wr, int wc, int fr, int fq) const {
;     ...
;                         u32x4 w; w.x = cvt_pk_bf16(v0[0], v0[1]); w.y = cvt_pk_bf16(v0[2], v0[3]); w.z = cvt_pk_bf16(v1[0], v1[1]); w.w = cvt_pk_bf16(v1[2], v1[3]);
;                         if (type == 1) *(u32x4*)(P + (size_t)row * 5120 + 1024 + (pnl - 8) * BM + bj * HALF + lc) = w;
;                         else { const int cg = (pnl - (type == 3 ? 12 : 16)) * BM + bj * HALF + lc;
;                             *(u32x4*)((type == 3 ? XB : ZB) + ((size_t)(cg >> 4) * 8448 + row) * 16 + (cg & 8)) = w; } }
.LBB0_494:
	v_ashrrev_i32_e32 v83, 31, v82
	v_cvt_pk_bf16_f32 v74, v84, v85
	v_cvt_pk_bf16_f32 v75, v80, v81
	v_cvt_pk_bf16_f32 v76, v76, v77
	v_cvt_pk_bf16_f32 v77, v86, v87
	s_and_b64 vcc, exec, s[8:9]
	s_mov_b64 s[88:89], -1
	s_cbranch_vccnz .LBB0_496
	v_ashrrev_i32_e32 v80, 4, v144
	s_and_b64 s[44:45], s[78:79], exec
	v_mad_i64_i32 v[80:81], s[88:89], v80, s41, v[82:83]
	s_cselect_b32 s45, s29, s53
	s_cselect_b32 s44, s28, s52
	v_lshlrev_b64 v[80:81], 5, v[80:81]
	v_lshl_add_u64 v[80:81], s[44:45], 0, v[80:81]
	v_lshlrev_b32_e32 v84, 1, v174
	v_mov_b32_e32 v85, v173
	v_lshl_add_u64 v[80:81], v[80:81], 0, v[84:85]
	s_mov_b64 s[88:89], 0
	global_store_dwordx4 v[80:81], v[74:77], off sc0 sc1
.LBB0_496:
	v_mad_i64_i32 v[80:81], s[44:45], v82, s40, 0
	s_andn2_b64 vcc, exec, s[88:89]
	v_lshl_add_u64 v[80:81], s[14:15], 0, v[80:81]
	s_cbranch_vccnz .LBB0_498
	s_lshl_b32 s34, s67, 1
	v_lshl_add_u64 v[84:85], v[80:81], 0, s[34:35]
	v_lshl_add_u64 v[84:85], v[84:85], 0, v[172:173]
	global_store_dwordx4 v[84:85], v[74:77], off offset:-2048 sc0 sc1

; __device__ __forceinline__ unsigned cvt_pk_bf16(float lo, float hi) { const f32x2_t v = {lo, hi}; return __builtin_bit_cast(unsigned, __builtin_convertvector(v, bf16x2_t)); }
;     __device__ __forceinline__ void operator()(const f32x4 (&acc)[2][2][4][2], const Unit& u, int wr, int wc, int fr, int fq) const {
;     ...
;                         u32x4 w; w.x = cvt_pk_bf16(v0[0], v0[1]); w.y = cvt_pk_bf16(v0[2], v0[3]); w.z = cvt_pk_bf16(v1[0], v1[1]); w.w = cvt_pk_bf16(v1[2], v1[3]);
;                         if (type == 1) *(u32x4*)(P + (size_t)row * 5120 + 1024 + (pnl - 8) * BM + bj * HALF + lc) = w;
;                         else { const int cg = (pnl - (type == 3 ? 12 : 16)) * BM + bj * HALF + lc;
;                             *(u32x4*)((type == 3 ? XB : ZB) + ((size_t)(cg >> 4) * 8448 + row) * 16 + (cg & 8)) = w; } }
.LBB0_502:
	v_cvt_pk_bf16_f32 v66, v70, v71
	v_cvt_pk_bf16_f32 v67, v72, v73
	v_cvt_pk_bf16_f32 v68, v68, v69
	v_cvt_pk_bf16_f32 v69, v74, v75
	s_and_b64 vcc, exec, s[8:9]
	s_mov_b64 s[8:9], -1
	s_cbranch_vccnz .LBB0_510
	v_ashrrev_i32_e32 v70, 4, v144
	v_or_b32_e32 v70, 8, v70
	s_and_b64 s[8:9], s[78:79], exec
	v_mad_i64_i32 v[70:71], s[44:45], v70, s41, v[82:83]
	s_cselect_b32 s9, s29, s53
	s_cselect_b32 s8, s28, s52
	v_lshlrev_b64 v[70:71], 5, v[70:71]
	v_lshl_add_u64 v[70:71], s[8:9], 0, v[70:71]
	v_lshlrev_b32_e32 v72, 1, v174
	v_mov_b32_e32 v73, v173
	v_lshl_add_u64 v[70:71], v[70:71], 0, v[72:73]
	global_store_dwordx4 v[70:71], v[66:69], off sc0 sc1
	s_cbranch_execz .LBB0_511

; __device__ __forceinline__ unsigned cvt_pk_bf16(float lo, float hi) { const f32x2_t v = {lo, hi}; return __builtin_bit_cast(unsigned, __builtin_convertvector(v, bf16x2_t)); }
;     __device__ __forceinline__ void operator()(const f32x4 (&acc)[2][2][4][2], const Unit& u, int wr, int wc, int fr, int fq) const {
;     ...
;                         u32x4 w; w.x = cvt_pk_bf16(v0[0], v0[1]); w.y = cvt_pk_bf16(v0[2], v0[3]); w.z = cvt_pk_bf16(v1[0], v1[1]); w.w = cvt_pk_bf16(v1[2], v1[3]);
;                         if (type == 1) *(u32x4*)(P + (size_t)row * 5120 + 1024 + (pnl - 8) * BM + bj * HALF + lc) = w;
.LBB0_511:
	s_lshl_b32 s34, s67, 1
	v_lshl_add_u64 v[70:71], v[80:81], 0, s[34:35]
	v_lshl_add_u64 v[70:71], v[70:71], 0, v[172:173]
	global_store_dwordx4 v[70:71], v[66:69], off offset:-1792 sc0 sc1
	s_andn2_b64 vcc, exec, s[76:77]
	s_cbranch_vccz .LBB0_505

; __device__ __forceinline__ unsigned cvt_pk_bf16(float lo, float hi) { const f32x2_t v = {lo, hi}; return __builtin_bit_cast(unsigned, __builtin_convertvector(v, bf16x2_t)); }
; __device__ __forceinline__ float silu_f(float x) { return x * __builtin_amdgcn_rcpf(1.0f + __expf(-x)); }
;     __device__ __forceinline__ void operator()(const f32x4 (&acc)[2][2][4][2], const Unit& u, int wr, int wc, int fr, int fq) const {
;     ...
;             for (int m = 0; m < 4; ++m) { const int row = row0 + ai * HALF + m * 16;
;                 if (type == 0) { f32x4 p0, p1;
; #pragma unroll
;                     for (int j = 0; j < 4; ++j) { p0[j] = (acc[ai][0][m][0][j] * osc) * silu_f(acc[ai][1][m][0][j] * osc); p1[j] = (acc[ai][0][m][1][j] * osc) * silu_f(acc[ai][1][m][1][j] * osc); }
;                     u32x4 w; w.x = cvt_pk_bf16(p0[0], p0[1]); w.y = cvt_pk_bf16(p0[2], p0[3]); w.z = cvt_pk_bf16(p1[0], p1[1]); w.w = cvt_pk_bf16(p1[2], p1[3]);
;                     *(u32x4*)(P + (size_t)row * 5120 + pnl * HALF + lc) = w; }
.LBB0_513:
	s_waitcnt lgkmcnt(0)
	v_pk_mul_f32 v[68:69], v[134:135], v[54:55]
	v_pk_mul_f32 v[72:73], v[134:135], v[62:63]
	v_mul_f32_e32 v67, 0xbfb8aa3b, v68
	v_exp_f32_e32 v67, v67
	v_pk_mul_f32 v[74:75], v[134:135], v[58:59]
	v_pk_mul_f32 v[76:77], v[134:135], v[64:65]
	v_pk_mul_f32 v[78:79], v[134:135], v[60:61]
	v_add_f32_e32 v67, 1.0, v67
	v_rcp_f32_e32 v70, v67
	v_mul_f32_e32 v67, 0xbfb8aa3b, v69
	v_exp_f32_e32 v67, v67
	s_nop 0
	v_add_f32_e32 v67, 1.0, v67
	v_rcp_f32_e32 v71, v67
	s_nop 0
	v_pk_mul_f32 v[68:69], v[68:69], v[70:71]
	v_pk_mul_f32 v[70:71], v[134:135], v[50:51]
	v_pk_mul_f32 v[68:69], v[68:69], v[72:73]
	v_mul_f32_e32 v67, 0xbfb8aa3b, v70
	v_exp_f32_e32 v67, v67
	v_cvt_pk_bf16_f32 v68, v68, v69
	v_add_f32_e32 v67, 1.0, v67
	v_rcp_f32_e32 v72, v67
	v_mul_f32_e32 v67, 0xbfb8aa3b, v71
	v_exp_f32_e32 v67, v67
	s_nop 0
	v_add_f32_e32 v67, 1.0, v67
	v_rcp_f32_e32 v73, v67
	s_nop 0
	v_pk_mul_f32 v[70:71], v[70:71], v[72:73]
	v_pk_mul_f32 v[72:73], v[134:135], v[56:57]
	v_pk_mul_f32 v[70:71], v[70:71], v[74:75]
	v_mul_f32_e32 v67, 0xbfb8aa3b, v72
	v_exp_f32_e32 v67, v67
	v_cvt_pk_bf16_f32 v70, v70, v71
	v_add_f32_e32 v67, 1.0, v67
	v_rcp_f32_e32 v74, v67
	v_mul_f32_e32 v67, 0xbfb8aa3b, v73
	v_exp_f32_e32 v67, v67
	s_nop 0
	v_add_f32_e32 v67, 1.0, v67
	v_rcp_f32_e32 v75, v67
	s_nop 0
	v_pk_mul_f32 v[72:73], v[72:73], v[74:75]
	v_pk_mul_f32 v[74:75], v[134:135], v[52:53]
	v_pk_mul_f32 v[72:73], v[72:73], v[76:77]
	v_mul_f32_e32 v67, 0xbfb8aa3b, v74
	v_exp_f32_e32 v67, v67
	v_cvt_pk_bf16_f32 v69, v72, v73
	v_mov_b64_e32 v[72:73], s[14:15]
	v_mad_i64_i32 v[72:73], s[8:9], v66, s40, v[72:73]
	v_add_f32_e32 v67, 1.0, v67
	v_rcp_f32_e32 v76, v67
	v_mul_f32_e32 v67, 0xbfb8aa3b, v75
	v_exp_f32_e32 v67, v67
	v_lshl_add_u64 v[72:73], s[86:87], 1, v[72:73]
	v_lshl_add_u64 v[72:73], v[72:73], 0, v[172:173]
	s_mov_b64 s[8:9], 0
	v_add_f32_e32 v67, 1.0, v67
	v_rcp_f32_e32 v77, v67
	s_nop 0
	v_pk_mul_f32 v[74:75], v[74:75], v[76:77]
	s_nop 0
	v_pk_mul_f32 v[74:75], v[74:75], v[78:79]
	s_nop 0
	v_cvt_pk_bf16_f32 v71, v74, v75
	global_store_dwordx4 v[72:73], v[68:71], off sc0 sc1

; __device__ __forceinline__ unsigned cvt_pk_bf16(float lo, float hi) { const f32x2_t v = {lo, hi}; return __builtin_bit_cast(unsigned, __builtin_convertvector(v, bf16x2_t)); }
;     __device__ __forceinline__ void operator()(const f32x4 (&acc)[2][2][4][2], const Unit& u, int wr, int wc, int fr, int fq) const {
;     ...
;                         u32x4 w; w.x = cvt_pk_bf16(v0[0], v0[1]); w.y = cvt_pk_bf16(v0[2], v0[3]); w.z = cvt_pk_bf16(v1[0], v1[1]); w.w = cvt_pk_bf16(v1[2], v1[3]);
;                         if (type == 1) *(u32x4*)(P + (size_t)row * 5120 + 1024 + (pnl - 8) * BM + bj * HALF + lc) = w;
;                         else { const int cg = (pnl - (type == 3 ? 12 : 16)) * BM + bj * HALF + lc;
;                             *(u32x4*)((type == 3 ? XB : ZB) + ((size_t)(cg >> 4) * 8448 + row) * 16 + (cg & 8)) = w; } }
.LBB0_522:
	v_ashrrev_i32_e32 v67, 31, v66
	v_cvt_pk_bf16_f32 v58, v68, v69
	v_cvt_pk_bf16_f32 v59, v64, v65
	v_cvt_pk_bf16_f32 v60, v60, v61
	v_cvt_pk_bf16_f32 v61, v70, v71
	s_and_b64 vcc, exec, s[8:9]
	s_mov_b64 s[88:89], -1
	s_cbranch_vccnz .LBB0_524
	v_ashrrev_i32_e32 v64, 4, v144
	s_and_b64 s[44:45], s[78:79], exec
	v_mad_i64_i32 v[64:65], s[88:89], v64, s41, v[66:67]
	s_cselect_b32 s45, s29, s53
	s_cselect_b32 s44, s28, s52
	v_lshlrev_b64 v[64:65], 5, v[64:65]
	v_lshl_add_u64 v[64:65], s[44:45], 0, v[64:65]
	v_lshlrev_b32_e32 v68, 1, v174
	v_mov_b32_e32 v69, v173
	v_lshl_add_u64 v[64:65], v[64:65], 0, v[68:69]
	s_mov_b64 s[88:89], 0
	global_store_dwordx4 v[64:65], v[58:61], off sc0 sc1
.LBB0_524:
	v_mad_i64_i32 v[64:65], s[44:45], v66, s40, 0
	s_andn2_b64 vcc, exec, s[88:89]
	v_lshl_add_u64 v[64:65], s[14:15], 0, v[64:65]
	s_cbranch_vccnz .LBB0_526
	s_lshl_b32 s34, s67, 1
	v_lshl_add_u64 v[68:69], v[64:65], 0, s[34:35]
	v_lshl_add_u64 v[68:69], v[68:69], 0, v[172:173]
	global_store_dwordx4 v[68:69], v[58:61], off offset:-2048 sc0 sc1

; __device__ __forceinline__ unsigned cvt_pk_bf16(float lo, float hi) { const f32x2_t v = {lo, hi}; return __builtin_bit_cast(unsigned, __builtin_convertvector(v, bf16x2_t)); }
;     __device__ __forceinline__ void operator()(const f32x4 (&acc)[2][2][4][2], const Unit& u, int wr, int wc, int fr, int fq) const {
;     ...
;                         u32x4 w; w.x = cvt_pk_bf16(v0[0], v0[1]); w.y = cvt_pk_bf16(v0[2], v0[3]); w.z = cvt_pk_bf16(v1[0], v1[1]); w.w = cvt_pk_bf16(v1[2], v1[3]);
;                         if (type == 1) *(u32x4*)(P + (size_t)row * 5120 + 1024 + (pnl - 8) * BM + bj * HALF + lc) = w;
;                         else { const int cg = (pnl - (type == 3 ? 12 : 16)) * BM + bj * HALF + lc;
;                             *(u32x4*)((type == 3 ? XB : ZB) + ((size_t)(cg >> 4) * 8448 + row) * 16 + (cg & 8)) = w; } }
.LBB0_530:
	v_cvt_pk_bf16_f32 v50, v54, v55
	v_cvt_pk_bf16_f32 v51, v56, v57
	v_cvt_pk_bf16_f32 v52, v52, v53
	v_cvt_pk_bf16_f32 v53, v58, v59
	s_and_b64 vcc, exec, s[8:9]
	s_mov_b64 s[8:9], -1
	s_cbranch_vccnz .LBB0_538
	v_ashrrev_i32_e32 v54, 4, v144
	v_or_b32_e32 v54, 8, v54
	s_and_b64 s[8:9], s[78:79], exec
	v_mad_i64_i32 v[54:55], s[44:45], v54, s41, v[66:67]
	s_cselect_b32 s9, s29, s53
	s_cselect_b32 s8, s28, s52
	v_lshlrev_b64 v[54:55], 5, v[54:55]
	v_lshl_add_u64 v[54:55], s[8:9], 0, v[54:55]
	v_lshlrev_b32_e32 v56, 1, v174
	v_mov_b32_e32 v57, v173
	v_lshl_add_u64 v[54:55], v[54:55], 0, v[56:57]
	global_store_dwordx4 v[54:55], v[50:53], off sc0 sc1
	s_cbranch_execz .LBB0_539

; __device__ __forceinline__ unsigned cvt_pk_bf16(float lo, float hi) { const f32x2_t v = {lo, hi}; return __builtin_bit_cast(unsigned, __builtin_convertvector(v, bf16x2_t)); }
;     __device__ __forceinline__ void operator()(const f32x4 (&acc)[2][2][4][2], const Unit& u, int wr, int wc, int fr, int fq) const {
;     ...
;                         u32x4 w; w.x = cvt_pk_bf16(v0[0], v0[1]); w.y = cvt_pk_bf16(v0[2], v0[3]); w.z = cvt_pk_bf16(v1[0], v1[1]); w.w = cvt_pk_bf16(v1[2], v1[3]);
;                         if (type == 1) *(u32x4*)(P + (size_t)row * 5120 + 1024 + (pnl - 8) * BM + bj * HALF + lc) = w;
.LBB0_539:
	s_lshl_b32 s34, s67, 1
	v_lshl_add_u64 v[54:55], v[64:65], 0, s[34:35]
	v_lshl_add_u64 v[54:55], v[54:55], 0, v[172:173]
	global_store_dwordx4 v[54:55], v[50:53], off offset:-1792 sc0 sc1
	s_andn2_b64 vcc, exec, s[76:77]
	s_cbranch_vccz .LBB0_533

; __device__ __forceinline__ unsigned cvt_pk_bf16(float lo, float hi) { const f32x2_t v = {lo, hi}; return __builtin_bit_cast(unsigned, __builtin_convertvector(v, bf16x2_t)); }
; __device__ __forceinline__ float silu_f(float x) { return x * __builtin_amdgcn_rcpf(1.0f + __expf(-x)); }
;     __device__ __forceinline__ void operator()(const f32x4 (&acc)[2][2][4][2], const Unit& u, int wr, int wc, int fr, int fq) const {
;     ...
;             for (int m = 0; m < 4; ++m) { const int row = row0 + ai * HALF + m * 16;
;                 if (type == 0) { f32x4 p0, p1;
; #pragma unroll
;                     for (int j = 0; j < 4; ++j) { p0[j] = (acc[ai][0][m][0][j] * osc) * silu_f(acc[ai][1][m][0][j] * osc); p1[j] = (acc[ai][0][m][1][j] * osc) * silu_f(acc[ai][1][m][1][j] * osc); }
;                     u32x4 w; w.x = cvt_pk_bf16(p0[0], p0[1]); w.y = cvt_pk_bf16(p0[2], p0[3]); w.z = cvt_pk_bf16(p1[0], p1[1]); w.w = cvt_pk_bf16(p1[2], p1[3]);
;                     *(u32x4*)(P + (size_t)row * 5120 + pnl * HALF + lc) = w; }
.LBB0_541:
	s_waitcnt lgkmcnt(0)
	v_pk_mul_f32 v[52:53], v[134:135], v[38:39]
	v_pk_mul_f32 v[56:57], v[134:135], v[46:47]
	v_mul_f32_e32 v51, 0xbfb8aa3b, v52
	v_exp_f32_e32 v51, v51
	v_pk_mul_f32 v[58:59], v[134:135], v[42:43]
	v_pk_mul_f32 v[60:61], v[134:135], v[48:49]
	v_pk_mul_f32 v[62:63], v[134:135], v[44:45]
	v_add_f32_e32 v51, 1.0, v51
	v_rcp_f32_e32 v54, v51
	v_mul_f32_e32 v51, 0xbfb8aa3b, v53
	v_exp_f32_e32 v51, v51
	s_nop 0
	v_add_f32_e32 v51, 1.0, v51
	v_rcp_f32_e32 v55, v51
	s_nop 0
	v_pk_mul_f32 v[52:53], v[52:53], v[54:55]
	v_pk_mul_f32 v[54:55], v[134:135], v[34:35]
	v_pk_mul_f32 v[52:53], v[52:53], v[56:57]
	v_mul_f32_e32 v51, 0xbfb8aa3b, v54
	v_exp_f32_e32 v51, v51
	v_cvt_pk_bf16_f32 v52, v52, v53
	v_add_f32_e32 v51, 1.0, v51
	v_rcp_f32_e32 v56, v51
	v_mul_f32_e32 v51, 0xbfb8aa3b, v55
	v_exp_f32_e32 v51, v51
	s_nop 0
	v_add_f32_e32 v51, 1.0, v51
	v_rcp_f32_e32 v57, v51
	s_nop 0
	v_pk_mul_f32 v[54:55], v[54:55], v[56:57]
	v_pk_mul_f32 v[56:57], v[134:135], v[40:41]
	v_pk_mul_f32 v[54:55], v[54:55], v[58:59]
	v_mul_f32_e32 v51, 0xbfb8aa3b, v56
	v_exp_f32_e32 v51, v51
	v_cvt_pk_bf16_f32 v54, v54, v55
	v_add_f32_e32 v51, 1.0, v51
	v_rcp_f32_e32 v58, v51
	v_mul_f32_e32 v51, 0xbfb8aa3b, v57
	v_exp_f32_e32 v51, v51
	s_nop 0
	v_add_f32_e32 v51, 1.0, v51
	v_rcp_f32_e32 v59, v51
	s_nop 0
	v_pk_mul_f32 v[56:57], v[56:57], v[58:59]
	v_pk_mul_f32 v[58:59], v[134:135], v[36:37]
	v_pk_mul_f32 v[56:57], v[56:57], v[60:61]
	v_mul_f32_e32 v51, 0xbfb8aa3b, v58
	v_exp_f32_e32 v51, v51
	v_cvt_pk_bf16_f32 v53, v56, v57
	v_mov_b64_e32 v[56:57], s[14:15]
	v_mad_i64_i32 v[56:57], s[8:9], v50, s40, v[56:57]
	v_add_f32_e32 v51, 1.0, v51
	v_rcp_f32_e32 v60, v51
	v_mul_f32_e32 v51, 0xbfb8aa3b, v59
	v_exp_f32_e32 v51, v51
	v_lshl_add_u64 v[56:57], s[86:87], 1, v[56:57]
	v_lshl_add_u64 v[56:57], v[56:57], 0, v[172:173]
	s_mov_b64 s[8:9], 0
	v_add_f32_e32 v51, 1.0, v51
	v_rcp_f32_e32 v61, v51
	s_nop 0
	v_pk_mul_f32 v[58:59], v[58:59], v[60:61]
	s_nop 0
	v_pk_mul_f32 v[58:59], v[58:59], v[62:63]
	s_nop 0
	v_cvt_pk_bf16_f32 v55, v58, v59
	global_store_dwordx4 v[56:57], v[52:55], off sc0 sc1

; __device__ __forceinline__ unsigned cvt_pk_bf16(float lo, float hi) { const f32x2_t v = {lo, hi}; return __builtin_bit_cast(unsigned, __builtin_convertvector(v, bf16x2_t)); }
;     __device__ __forceinline__ void operator()(const f32x4 (&acc)[2][2][4][2], const Unit& u, int wr, int wc, int fr, int fq) const {
;     ...
;                         u32x4 w; w.x = cvt_pk_bf16(v0[0], v0[1]); w.y = cvt_pk_bf16(v0[2], v0[3]); w.z = cvt_pk_bf16(v1[0], v1[1]); w.w = cvt_pk_bf16(v1[2], v1[3]);
;                         if (type == 1) *(u32x4*)(P + (size_t)row * 5120 + 1024 + (pnl - 8) * BM + bj * HALF + lc) = w;
;                         else { const int cg = (pnl - (type == 3 ? 12 : 16)) * BM + bj * HALF + lc;
;                             *(u32x4*)((type == 3 ? XB : ZB) + ((size_t)(cg >> 4) * 8448 + row) * 16 + (cg & 8)) = w; } }
.LBB0_550:
	v_ashrrev_i32_e32 v51, 31, v50
	v_cvt_pk_bf16_f32 v42, v52, v53
	v_cvt_pk_bf16_f32 v43, v48, v49
	v_cvt_pk_bf16_f32 v44, v44, v45
	v_cvt_pk_bf16_f32 v45, v54, v55
	s_and_b64 vcc, exec, s[8:9]
	s_mov_b64 s[88:89], -1
	s_cbranch_vccnz .LBB0_552
	v_ashrrev_i32_e32 v48, 4, v144
	s_and_b64 s[44:45], s[78:79], exec
	v_mad_i64_i32 v[48:49], s[88:89], v48, s41, v[50:51]
	s_cselect_b32 s45, s29, s53
	s_cselect_b32 s44, s28, s52
	v_lshlrev_b64 v[48:49], 5, v[48:49]
	v_lshl_add_u64 v[48:49], s[44:45], 0, v[48:49]
	v_lshlrev_b32_e32 v52, 1, v174
	v_mov_b32_e32 v53, v173
	v_lshl_add_u64 v[48:49], v[48:49], 0, v[52:53]
	s_mov_b64 s[88:89], 0
	global_store_dwordx4 v[48:49], v[42:45], off sc0 sc1
.LBB0_552:
	v_mad_i64_i32 v[48:49], s[44:45], v50, s40, 0
	s_andn2_b64 vcc, exec, s[88:89]
	v_lshl_add_u64 v[48:49], s[14:15], 0, v[48:49]
	s_cbranch_vccnz .LBB0_554
	s_lshl_b32 s34, s67, 1
	v_lshl_add_u64 v[52:53], v[48:49], 0, s[34:35]
	v_lshl_add_u64 v[52:53], v[52:53], 0, v[172:173]
	global_store_dwordx4 v[52:53], v[42:45], off offset:-2048 sc0 sc1

; __device__ __forceinline__ unsigned cvt_pk_bf16(float lo, float hi) { const f32x2_t v = {lo, hi}; return __builtin_bit_cast(unsigned, __builtin_convertvector(v, bf16x2_t)); }
;     __device__ __forceinline__ void operator()(const f32x4 (&acc)[2][2][4][2], const Unit& u, int wr, int wc, int fr, int fq) const {
;     ...
;                         u32x4 w; w.x = cvt_pk_bf16(v0[0], v0[1]); w.y = cvt_pk_bf16(v0[2], v0[3]); w.z = cvt_pk_bf16(v1[0], v1[1]); w.w = cvt_pk_bf16(v1[2], v1[3]);
;                         if (type == 1) *(u32x4*)(P + (size_t)row * 5120 + 1024 + (pnl - 8) * BM + bj * HALF + lc) = w;
;                         else { const int cg = (pnl - (type == 3 ? 12 : 16)) * BM + bj * HALF + lc;
;                             *(u32x4*)((type == 3 ? XB : ZB) + ((size_t)(cg >> 4) * 8448 + row) * 16 + (cg & 8)) = w; } }
.LBB0_558:
	v_cvt_pk_bf16_f32 v34, v38, v39
	v_cvt_pk_bf16_f32 v35, v40, v41
	v_cvt_pk_bf16_f32 v36, v36, v37
	v_cvt_pk_bf16_f32 v37, v42, v43
	s_and_b64 vcc, exec, s[8:9]
	s_mov_b64 s[8:9], -1
	s_cbranch_vccnz .LBB0_566
	v_ashrrev_i32_e32 v38, 4, v144
	v_or_b32_e32 v38, 8, v38
	s_and_b64 s[8:9], s[78:79], exec
	v_mad_i64_i32 v[38:39], s[44:45], v38, s41, v[50:51]
	s_cselect_b32 s9, s29, s53
	s_cselect_b32 s8, s28, s52
	v_lshlrev_b64 v[38:39], 5, v[38:39]
	v_lshl_add_u64 v[38:39], s[8:9], 0, v[38:39]
	v_lshlrev_b32_e32 v40, 1, v174
	v_mov_b32_e32 v41, v173
	v_lshl_add_u64 v[38:39], v[38:39], 0, v[40:41]
	global_store_dwordx4 v[38:39], v[34:37], off sc0 sc1
	s_cbranch_execz .LBB0_567

; __device__ __forceinline__ unsigned cvt_pk_bf16(float lo, float hi) { const f32x2_t v = {lo, hi}; return __builtin_bit_cast(unsigned, __builtin_convertvector(v, bf16x2_t)); }
;     __device__ __forceinline__ void operator()(const f32x4 (&acc)[2][2][4][2], const Unit& u, int wr, int wc, int fr, int fq) const {
;     ...
;                         u32x4 w; w.x = cvt_pk_bf16(v0[0], v0[1]); w.y = cvt_pk_bf16(v0[2], v0[3]); w.z = cvt_pk_bf16(v1[0], v1[1]); w.w = cvt_pk_bf16(v1[2], v1[3]);
;                         if (type == 1) *(u32x4*)(P + (size_t)row * 5120 + 1024 + (pnl - 8) * BM + bj * HALF + lc) = w;
.LBB0_567:
	s_lshl_b32 s34, s67, 1
	v_lshl_add_u64 v[38:39], v[48:49], 0, s[34:35]
	v_lshl_add_u64 v[38:39], v[38:39], 0, v[172:173]
	global_store_dwordx4 v[38:39], v[34:37], off offset:-1792 sc0 sc1
	s_andn2_b64 vcc, exec, s[76:77]
	s_cbranch_vccz .LBB0_561

; __device__ __forceinline__ unsigned cvt_pk_bf16(float lo, float hi) { const f32x2_t v = {lo, hi}; return __builtin_bit_cast(unsigned, __builtin_convertvector(v, bf16x2_t)); }
; __device__ __forceinline__ float silu_f(float x) { return x * __builtin_amdgcn_rcpf(1.0f + __expf(-x)); }
;     __device__ __forceinline__ void operator()(const f32x4 (&acc)[2][2][4][2], const Unit& u, int wr, int wc, int fr, int fq) const {
;     ...
;             for (int m = 0; m < 4; ++m) { const int row = row0 + ai * HALF + m * 16;
;                 if (type == 0) { f32x4 p0, p1;
; #pragma unroll
;                     for (int j = 0; j < 4; ++j) { p0[j] = (acc[ai][0][m][0][j] * osc) * silu_f(acc[ai][1][m][0][j] * osc); p1[j] = (acc[ai][0][m][1][j] * osc) * silu_f(acc[ai][1][m][1][j] * osc); }
;                     u32x4 w; w.x = cvt_pk_bf16(p0[0], p0[1]); w.y = cvt_pk_bf16(p0[2], p0[3]); w.z = cvt_pk_bf16(p1[0], p1[1]); w.w = cvt_pk_bf16(p1[2], p1[3]);
;                     *(u32x4*)(P + (size_t)row * 5120 + pnl * HALF + lc) = w; }
.LBB0_569:
	s_waitcnt lgkmcnt(0)
	v_pk_mul_f32 v[36:37], v[134:135], v[22:23]
	v_pk_mul_f32 v[40:41], v[134:135], v[30:31]
	v_mul_f32_e32 v35, 0xbfb8aa3b, v36
	v_exp_f32_e32 v35, v35
	v_pk_mul_f32 v[42:43], v[134:135], v[26:27]
	v_pk_mul_f32 v[44:45], v[134:135], v[32:33]
	v_pk_mul_f32 v[46:47], v[134:135], v[28:29]
	v_add_f32_e32 v35, 1.0, v35
	v_rcp_f32_e32 v38, v35
	v_mul_f32_e32 v35, 0xbfb8aa3b, v37
	v_exp_f32_e32 v35, v35
	s_nop 0
	v_add_f32_e32 v35, 1.0, v35
	v_rcp_f32_e32 v39, v35
	s_nop 0
	v_pk_mul_f32 v[36:37], v[36:37], v[38:39]
	v_pk_mul_f32 v[38:39], v[134:135], v[18:19]
	v_pk_mul_f32 v[36:37], v[36:37], v[40:41]
	v_mul_f32_e32 v35, 0xbfb8aa3b, v38
	v_exp_f32_e32 v35, v35
	v_cvt_pk_bf16_f32 v36, v36, v37
	v_add_f32_e32 v35, 1.0, v35
	v_rcp_f32_e32 v40, v35
	v_mul_f32_e32 v35, 0xbfb8aa3b, v39
	v_exp_f32_e32 v35, v35
	s_nop 0
	v_add_f32_e32 v35, 1.0, v35
	v_rcp_f32_e32 v41, v35
	s_nop 0
	v_pk_mul_f32 v[38:39], v[38:39], v[40:41]
	v_pk_mul_f32 v[40:41], v[134:135], v[24:25]
	v_pk_mul_f32 v[38:39], v[38:39], v[42:43]
	v_mul_f32_e32 v35, 0xbfb8aa3b, v40
	v_exp_f32_e32 v35, v35
	v_cvt_pk_bf16_f32 v38, v38, v39
	v_add_f32_e32 v35, 1.0, v35
	v_rcp_f32_e32 v42, v35
	v_mul_f32_e32 v35, 0xbfb8aa3b, v41
	v_exp_f32_e32 v35, v35
	s_nop 0
	v_add_f32_e32 v35, 1.0, v35
	v_rcp_f32_e32 v43, v35
	s_nop 0
	v_pk_mul_f32 v[40:41], v[40:41], v[42:43]
	v_pk_mul_f32 v[42:43], v[134:135], v[20:21]
	v_pk_mul_f32 v[40:41], v[40:41], v[44:45]
	v_mul_f32_e32 v35, 0xbfb8aa3b, v42
	v_exp_f32_e32 v35, v35
	v_cvt_pk_bf16_f32 v37, v40, v41
	v_mov_b64_e32 v[40:41], s[14:15]
	v_mad_i64_i32 v[40:41], s[8:9], v34, s40, v[40:41]
	v_add_f32_e32 v35, 1.0, v35
	v_rcp_f32_e32 v44, v35
	v_mul_f32_e32 v35, 0xbfb8aa3b, v43
	v_exp_f32_e32 v35, v35
	v_lshl_add_u64 v[40:41], s[86:87], 1, v[40:41]
	v_lshl_add_u64 v[40:41], v[40:41], 0, v[172:173]
	s_mov_b64 s[8:9], 0
	v_add_f32_e32 v35, 1.0, v35
	v_rcp_f32_e32 v45, v35
	s_nop 0
	v_pk_mul_f32 v[42:43], v[42:43], v[44:45]
	s_nop 0
	v_pk_mul_f32 v[42:43], v[42:43], v[46:47]
	s_nop 0
	v_cvt_pk_bf16_f32 v39, v42, v43
	global_store_dwordx4 v[40:41], v[36:39], off sc0 sc1

; __device__ __forceinline__ unsigned cvt_pk_bf16(float lo, float hi) { const f32x2_t v = {lo, hi}; return __builtin_bit_cast(unsigned, __builtin_convertvector(v, bf16x2_t)); }
;     __device__ __forceinline__ void operator()(const f32x4 (&acc)[2][2][4][2], const Unit& u, int wr, int wc, int fr, int fq) const {
;     ...
;                         u32x4 w; w.x = cvt_pk_bf16(v0[0], v0[1]); w.y = cvt_pk_bf16(v0[2], v0[3]); w.z = cvt_pk_bf16(v1[0], v1[1]); w.w = cvt_pk_bf16(v1[2], v1[3]);
;                         if (type == 1) *(u32x4*)(P + (size_t)row * 5120 + 1024 + (pnl - 8) * BM + bj * HALF + lc) = w;
;                         else { const int cg = (pnl - (type == 3 ? 12 : 16)) * BM + bj * HALF + lc;
;                             *(u32x4*)((type == 3 ? XB : ZB) + ((size_t)(cg >> 4) * 8448 + row) * 16 + (cg & 8)) = w; } }
.LBB0_578:
	v_ashrrev_i32_e32 v35, 31, v34
	v_cvt_pk_bf16_f32 v26, v36, v37
	v_cvt_pk_bf16_f32 v27, v32, v33
	v_cvt_pk_bf16_f32 v28, v28, v29
	v_cvt_pk_bf16_f32 v29, v38, v39
	s_and_b64 vcc, exec, s[8:9]
	s_mov_b64 s[88:89], -1
	s_cbranch_vccnz .LBB0_580
	v_ashrrev_i32_e32 v32, 4, v144
	s_and_b64 s[44:45], s[78:79], exec
	v_mad_i64_i32 v[32:33], s[88:89], v32, s41, v[34:35]
	s_cselect_b32 s45, s29, s53
	s_cselect_b32 s44, s28, s52
	v_lshlrev_b64 v[32:33], 5, v[32:33]
	v_lshl_add_u64 v[32:33], s[44:45], 0, v[32:33]
	v_lshlrev_b32_e32 v36, 1, v174
	v_mov_b32_e32 v37, v173
	v_lshl_add_u64 v[32:33], v[32:33], 0, v[36:37]
	s_mov_b64 s[88:89], 0
	global_store_dwordx4 v[32:33], v[26:29], off sc0 sc1
.LBB0_580:
	v_mad_i64_i32 v[32:33], s[44:45], v34, s40, 0
	s_andn2_b64 vcc, exec, s[88:89]
	v_lshl_add_u64 v[32:33], s[14:15], 0, v[32:33]
	s_cbranch_vccnz .LBB0_582
	s_lshl_b32 s34, s67, 1
	v_lshl_add_u64 v[36:37], v[32:33], 0, s[34:35]
	v_lshl_add_u64 v[36:37], v[36:37], 0, v[172:173]
	global_store_dwordx4 v[36:37], v[26:29], off offset:-2048 sc0 sc1

; __device__ __forceinline__ unsigned cvt_pk_bf16(float lo, float hi) { const f32x2_t v = {lo, hi}; return __builtin_bit_cast(unsigned, __builtin_convertvector(v, bf16x2_t)); }
;     __device__ __forceinline__ void operator()(const f32x4 (&acc)[2][2][4][2], const Unit& u, int wr, int wc, int fr, int fq) const {
;     ...
;                         u32x4 w; w.x = cvt_pk_bf16(v0[0], v0[1]); w.y = cvt_pk_bf16(v0[2], v0[3]); w.z = cvt_pk_bf16(v1[0], v1[1]); w.w = cvt_pk_bf16(v1[2], v1[3]);
;                         if (type == 1) *(u32x4*)(P + (size_t)row * 5120 + 1024 + (pnl - 8) * BM + bj * HALF + lc) = w;
;                         else { const int cg = (pnl - (type == 3 ? 12 : 16)) * BM + bj * HALF + lc;
;                             *(u32x4*)((type == 3 ? XB : ZB) + ((size_t)(cg >> 4) * 8448 + row) * 16 + (cg & 8)) = w; } }
.LBB0_586:
	v_cvt_pk_bf16_f32 v18, v22, v23
	v_cvt_pk_bf16_f32 v19, v24, v25
	v_cvt_pk_bf16_f32 v20, v20, v21
	v_cvt_pk_bf16_f32 v21, v26, v27
	s_and_b64 vcc, exec, s[8:9]
	s_mov_b64 s[8:9], -1
	s_cbranch_vccnz .LBB0_594
	v_ashrrev_i32_e32 v22, 4, v144
	v_or_b32_e32 v22, 8, v22
	s_and_b64 s[8:9], s[78:79], exec
	v_mad_i64_i32 v[22:23], s[44:45], v22, s41, v[34:35]
	s_cselect_b32 s9, s29, s53
	s_cselect_b32 s8, s28, s52
	v_lshlrev_b64 v[22:23], 5, v[22:23]
	v_lshl_add_u64 v[22:23], s[8:9], 0, v[22:23]
	v_lshlrev_b32_e32 v24, 1, v174
	v_mov_b32_e32 v25, v173
	v_lshl_add_u64 v[22:23], v[22:23], 0, v[24:25]
	global_store_dwordx4 v[22:23], v[18:21], off sc0 sc1
	s_cbranch_execz .LBB0_595

; __device__ __forceinline__ unsigned cvt_pk_bf16(float lo, float hi) { const f32x2_t v = {lo, hi}; return __builtin_bit_cast(unsigned, __builtin_convertvector(v, bf16x2_t)); }
;     __device__ __forceinline__ void operator()(const f32x4 (&acc)[2][2][4][2], const Unit& u, int wr, int wc, int fr, int fq) const {
;     ...
;                         u32x4 w; w.x = cvt_pk_bf16(v0[0], v0[1]); w.y = cvt_pk_bf16(v0[2], v0[3]); w.z = cvt_pk_bf16(v1[0], v1[1]); w.w = cvt_pk_bf16(v1[2], v1[3]);
;                         if (type == 1) *(u32x4*)(P + (size_t)row * 5120 + 1024 + (pnl - 8) * BM + bj * HALF + lc) = w;
.LBB0_595:
	s_lshl_b32 s34, s67, 1
	v_lshl_add_u64 v[22:23], v[32:33], 0, s[34:35]
	v_lshl_add_u64 v[22:23], v[22:23], 0, v[172:173]
	global_store_dwordx4 v[22:23], v[18:21], off offset:-1792 sc0 sc1
	s_andn2_b64 vcc, exec, s[76:77]
	s_cbranch_vccz .LBB0_589

; __device__ __forceinline__ unsigned cvt_pk_bf16(float lo, float hi) { const f32x2_t v = {lo, hi}; return __builtin_bit_cast(unsigned, __builtin_convertvector(v, bf16x2_t)); }
; __device__ __forceinline__ float silu_f(float x) { return x * __builtin_amdgcn_rcpf(1.0f + __expf(-x)); }
;     __device__ __forceinline__ void operator()(const f32x4 (&acc)[2][2][4][2], const Unit& u, int wr, int wc, int fr, int fq) const {
;     ...
;             for (int m = 0; m < 4; ++m) { const int row = row0 + ai * HALF + m * 16;
;                 if (type == 0) { f32x4 p0, p1;
; #pragma unroll
;                     for (int j = 0; j < 4; ++j) { p0[j] = (acc[ai][0][m][0][j] * osc) * silu_f(acc[ai][1][m][0][j] * osc); p1[j] = (acc[ai][0][m][1][j] * osc) * silu_f(acc[ai][1][m][1][j] * osc); }
;                     u32x4 w; w.x = cvt_pk_bf16(p0[0], p0[1]); w.y = cvt_pk_bf16(p0[2], p0[3]); w.z = cvt_pk_bf16(p1[0], p1[1]); w.w = cvt_pk_bf16(p1[2], p1[3]);
;                     *(u32x4*)(P + (size_t)row * 5120 + pnl * HALF + lc) = w; }
.LBB0_597:
	s_waitcnt lgkmcnt(0)
	v_pk_mul_f32 v[20:21], v[134:135], v[6:7]
	v_pk_mul_f32 v[24:25], v[134:135], v[14:15]
	v_mul_f32_e32 v19, 0xbfb8aa3b, v20
	v_exp_f32_e32 v19, v19
	v_pk_mul_f32 v[26:27], v[134:135], v[10:11]
	v_pk_mul_f32 v[28:29], v[134:135], v[16:17]
	v_pk_mul_f32 v[30:31], v[134:135], v[12:13]
	v_add_f32_e32 v19, 1.0, v19
	v_rcp_f32_e32 v22, v19
	v_mul_f32_e32 v19, 0xbfb8aa3b, v21
	v_exp_f32_e32 v19, v19
	s_nop 0
	v_add_f32_e32 v19, 1.0, v19
	v_rcp_f32_e32 v23, v19
	s_nop 0
	v_pk_mul_f32 v[20:21], v[20:21], v[22:23]
	v_pk_mul_f32 v[22:23], v[134:135], v[2:3]
	v_pk_mul_f32 v[20:21], v[20:21], v[24:25]
	v_mul_f32_e32 v19, 0xbfb8aa3b, v22
	v_exp_f32_e32 v19, v19
	v_cvt_pk_bf16_f32 v20, v20, v21
	v_add_f32_e32 v19, 1.0, v19
	v_rcp_f32_e32 v24, v19
	v_mul_f32_e32 v19, 0xbfb8aa3b, v23
	v_exp_f32_e32 v19, v19
	s_nop 0
	v_add_f32_e32 v19, 1.0, v19
	v_rcp_f32_e32 v25, v19
	s_nop 0
	v_pk_mul_f32 v[22:23], v[22:23], v[24:25]
	v_pk_mul_f32 v[24:25], v[134:135], v[8:9]
	v_pk_mul_f32 v[22:23], v[22:23], v[26:27]
	v_mul_f32_e32 v19, 0xbfb8aa3b, v24
	v_exp_f32_e32 v19, v19
	v_cvt_pk_bf16_f32 v22, v22, v23
	v_add_f32_e32 v19, 1.0, v19
	v_rcp_f32_e32 v26, v19
	v_mul_f32_e32 v19, 0xbfb8aa3b, v25
	v_exp_f32_e32 v19, v19
	s_nop 0
	v_add_f32_e32 v19, 1.0, v19
	v_rcp_f32_e32 v27, v19
	s_nop 0
	v_pk_mul_f32 v[24:25], v[24:25], v[26:27]
	v_pk_mul_f32 v[26:27], v[134:135], v[4:5]
	v_pk_mul_f32 v[24:25], v[24:25], v[28:29]
	v_mul_f32_e32 v19, 0xbfb8aa3b, v26
	v_exp_f32_e32 v19, v19
	v_cvt_pk_bf16_f32 v21, v24, v25
	v_mov_b64_e32 v[24:25], s[14:15]
	v_mad_i64_i32 v[24:25], s[6:7], v18, s40, v[24:25]
	v_add_f32_e32 v19, 1.0, v19
	v_rcp_f32_e32 v28, v19
	v_mul_f32_e32 v19, 0xbfb8aa3b, v27
	v_exp_f32_e32 v19, v19
	v_lshl_add_u64 v[24:25], s[86:87], 1, v[24:25]
	v_lshl_add_u64 v[24:25], v[24:25], 0, v[172:173]
	s_mov_b64 s[6:7], 0
	v_add_f32_e32 v19, 1.0, v19
	v_rcp_f32_e32 v29, v19
	s_nop 0
	v_pk_mul_f32 v[26:27], v[26:27], v[28:29]
	s_nop 0
	v_pk_mul_f32 v[26:27], v[26:27], v[30:31]
	s_nop 0
	v_cvt_pk_bf16_f32 v23, v26, v27
	global_store_dwordx4 v[24:25], v[20:23], off sc0 sc1

; __device__ __forceinline__ unsigned cvt_pk_bf16(float lo, float hi) { const f32x2_t v = {lo, hi}; return __builtin_bit_cast(unsigned, __builtin_convertvector(v, bf16x2_t)); }
;     __device__ __forceinline__ void operator()(const f32x4 (&acc)[2][2][4][2], const Unit& u, int wr, int wc, int fr, int fq) const {
;     ...
;                         u32x4 w; w.x = cvt_pk_bf16(v0[0], v0[1]); w.y = cvt_pk_bf16(v0[2], v0[3]); w.z = cvt_pk_bf16(v1[0], v1[1]); w.w = cvt_pk_bf16(v1[2], v1[3]);
;                         if (type == 1) *(u32x4*)(P + (size_t)row * 5120 + 1024 + (pnl - 8) * BM + bj * HALF + lc) = w;
;                         else { const int cg = (pnl - (type == 3 ? 12 : 16)) * BM + bj * HALF + lc;
;                             *(u32x4*)((type == 3 ? XB : ZB) + ((size_t)(cg >> 4) * 8448 + row) * 16 + (cg & 8)) = w; } }
.LBB0_606:
	v_ashrrev_i32_e32 v19, 31, v18
	v_cvt_pk_bf16_f32 v10, v20, v21
	v_cvt_pk_bf16_f32 v11, v16, v17
	v_cvt_pk_bf16_f32 v12, v12, v13
	v_cvt_pk_bf16_f32 v13, v22, v23
	s_mov_b64 s[8:9], -1
	s_and_b64 vcc, exec, s[6:7]
	v_ashrrev_i32_e32 v20, 4, v144
	s_cbranch_vccnz .LBB0_608
	s_and_b64 s[8:9], s[78:79], exec
	v_mad_i64_i32 v[16:17], s[44:45], v20, s41, v[18:19]
	s_cselect_b32 s9, s29, s53
	s_cselect_b32 s8, s28, s52
	v_lshlrev_b64 v[16:17], 5, v[16:17]
	v_lshl_add_u64 v[16:17], s[8:9], 0, v[16:17]
	v_lshlrev_b32_e32 v22, 1, v174
	v_mov_b32_e32 v23, v173
	v_lshl_add_u64 v[16:17], v[16:17], 0, v[22:23]
	s_mov_b64 s[8:9], 0
	global_store_dwordx4 v[16:17], v[10:13], off sc0 sc1
.LBB0_608:
	v_mad_i64_i32 v[16:17], s[44:45], v18, s40, 0
	s_andn2_b64 vcc, exec, s[8:9]
	v_lshl_add_u64 v[16:17], s[14:15], 0, v[16:17]
	s_cbranch_vccnz .LBB0_610
	s_lshl_b32 s34, s67, 1
	v_lshl_add_u64 v[22:23], v[16:17], 0, s[34:35]
	v_lshl_add_u64 v[22:23], v[22:23], 0, v[172:173]
	global_store_dwordx4 v[22:23], v[10:13], off offset:-2048 sc0 sc1

; __device__ __forceinline__ unsigned cvt_pk_bf16(float lo, float hi) { const f32x2_t v = {lo, hi}; return __builtin_bit_cast(unsigned, __builtin_convertvector(v, bf16x2_t)); }
;     __device__ __forceinline__ void operator()(const f32x4 (&acc)[2][2][4][2], const Unit& u, int wr, int wc, int fr, int fq) const {
;     ...
;                         u32x4 w; w.x = cvt_pk_bf16(v0[0], v0[1]); w.y = cvt_pk_bf16(v0[2], v0[3]); w.z = cvt_pk_bf16(v1[0], v1[1]); w.w = cvt_pk_bf16(v1[2], v1[3]);
;                         if (type == 1) *(u32x4*)(P + (size_t)row * 5120 + 1024 + (pnl - 8) * BM + bj * HALF + lc) = w;
;                         else { const int cg = (pnl - (type == 3 ? 12 : 16)) * BM + bj * HALF + lc;
;                             *(u32x4*)((type == 3 ? XB : ZB) + ((size_t)(cg >> 4) * 8448 + row) * 16 + (cg & 8)) = w; } }
.LBB0_614:
	v_cvt_pk_bf16_f32 v2, v6, v7
	v_cvt_pk_bf16_f32 v3, v8, v9
	v_cvt_pk_bf16_f32 v4, v4, v5
	v_cvt_pk_bf16_f32 v5, v10, v11
	s_and_b64 vcc, exec, s[6:7]
	s_mov_b64 s[4:5], -1
	s_cbranch_vccnz .LBB0_622
	v_or_b32_e32 v6, 8, v20
	s_and_b64 s[4:5], s[78:79], exec
	v_mad_i64_i32 v[6:7], s[6:7], v6, s41, v[18:19]
	s_cselect_b32 s5, s29, s53
	s_cselect_b32 s4, s28, s52
	v_lshlrev_b64 v[6:7], 5, v[6:7]
	v_lshl_add_u64 v[6:7], s[4:5], 0, v[6:7]
	v_lshlrev_b32_e32 v8, 1, v174
	v_mov_b32_e32 v9, v173
	v_lshl_add_u64 v[6:7], v[6:7], 0, v[8:9]
	global_store_dwordx4 v[6:7], v[2:5], off sc0 sc1
	s_cbranch_execz .LBB0_623

; __device__ __forceinline__ unsigned cvt_pk_bf16(float lo, float hi) { const f32x2_t v = {lo, hi}; return __builtin_bit_cast(unsigned, __builtin_convertvector(v, bf16x2_t)); }
;     __device__ __forceinline__ void operator()(const f32x4 (&acc)[2][2][4][2], const Unit& u, int wr, int wc, int fr, int fq) const {
;     ...
;                         u32x4 w; w.x = cvt_pk_bf16(v0[0], v0[1]); w.y = cvt_pk_bf16(v0[2], v0[3]); w.z = cvt_pk_bf16(v1[0], v1[1]); w.w = cvt_pk_bf16(v1[2], v1[3]);
;                         if (type == 1) *(u32x4*)(P + (size_t)row * 5120 + 1024 + (pnl - 8) * BM + bj * HALF + lc) = w;
.LBB0_623:
	s_lshl_b32 s34, s67, 1
	v_lshl_add_u64 v[6:7], v[16:17], 0, s[34:35]
	v_lshl_add_u64 v[6:7], v[6:7], 0, v[172:173]
	global_store_dwordx4 v[6:7], v[2:5], off offset:-1792 sc0 sc1
	s_andn2_b64 vcc, exec, s[76:77]
	s_cbranch_vccz .LBB0_617

; __device__ __forceinline__ unsigned cvt_pk_bf16(float lo, float hi) { const f32x2_t v = {lo, hi}; return __builtin_bit_cast(unsigned, __builtin_convertvector(v, bf16x2_t)); }
; __device__ __forceinline__ float silu_f(float x) { return x * __builtin_amdgcn_rcpf(1.0f + __expf(-x)); }
;     __device__ __forceinline__ void operator()(const f32x4 (&acc)[2][2][4][2], const Unit& u, int wr, int wc, int fr, int fq) const {
;         const int row0 = u.pm * BM + wr * 64 + fr, lc = wc * 32 + 8 * fq;
;         const int pnl = (f8tiles && u.pn >= 12) ? u.pn + 4 : u.pn;
;         const int type = (pnl < 8) ? 0 : (pnl < 12) ? 1 : (pnl < 16) ? 3 : 4;
; #pragma unroll
;         for (int ai = 0; ai < 2; ++ai)
; #pragma unroll
;             for (int m = 0; m < 4; ++m) { const int row = row0 + ai * HALF + m * 16;
;                 if (type == 0) { f32x4 p0, p1;
; #pragma unroll
;                     for (int j = 0; j < 4; ++j) { p0[j] = (acc[ai][0][m][0][j] * osc) * silu_f(acc[ai][1][m][0][j] * osc); p1[j] = (acc[ai][0][m][1][j] * osc) * silu_f(acc[ai][1][m][1][j] * osc); }
;                     u32x4 w; w.x = cvt_pk_bf16(p0[0], p0[1]); w.y = cvt_pk_bf16(p0[2], p0[3]); w.z = cvt_pk_bf16(p1[0], p1[1]); w.w = cvt_pk_bf16(p1[2], p1[3]);
;                     *(u32x4*)(P + (size_t)row * 5120 + pnl * HALF + lc) = w; }
.LBB0_665:
	v_lshl_add_u32 v6, s2, 8, v209
	s_add_i32 s2, s44, 4
	s_cmp_gt_i32 s44, 11
	s_cselect_b32 s2, s2, s44
	s_cmp_lt_i32 s2, 8
	s_cselect_b64 s[8:9], -1, 0
	s_cmp_lt_u32 s2, 16
	s_cselect_b32 s6, 3, 4
	s_cmp_lt_u32 s2, 12
	s_cselect_b64 s[76:77], -1, 0
	s_and_b64 s[4:5], s[76:77], exec
	s_cselect_b32 s6, 1, s6
	s_cmp_gt_i32 s2, 7
	s_cselect_b64 s[4:5], -1, 0
	s_and_b64 vcc, s[4:5], exec
	s_cselect_b32 s6, s6, 0
	s_lshl_b32 s86, s2, 7
	s_ashr_i32 s87, s86, 31
	s_cmp_eq_u32 s6, 4
	s_cselect_b64 s[4:5], -1, 0
	s_and_b32 s7, s2, 0x7ffffffc
	s_cmp_lg_u32 s7, 8
	s_cselect_b64 s[84:85], -1, 0
	s_cmp_eq_u32 s6, 3
	s_cselect_b64 s[78:79], -1, 0
	s_and_b64 s[6:7], s[78:79], exec
	s_cselect_b32 s33, -12, -16
	s_mov_b64 s[6:7], -1
	v_lshlrev_b32_e32 v172, 1, v186
	s_cbranch_vccnz .LBB0_667
	v_pk_mul_f32 v[2:3], v[190:191], v[150:151]
	v_pk_mul_f32 v[8:9], v[190:191], v[158:159]
	v_mul_f32_e32 v4, 0xbfb8aa3b, v2
	v_mul_f32_e32 v5, 0xbfb8aa3b, v3
	v_exp_f32_e32 v4, v4
	v_exp_f32_e32 v5, v5
	v_pk_mul_f32 v[10:11], v[190:191], v[154:155]
	v_pk_mul_f32 v[12:13], v[190:191], v[160:161]
	v_add_f32_e32 v4, 1.0, v4
	v_add_f32_e32 v5, 1.0, v5
	v_rcp_f32_e32 v4, v4
	v_rcp_f32_e32 v5, v5
	v_pk_mul_f32 v[14:15], v[190:191], v[156:157]
	v_pk_mul_f32 v[2:3], v[2:3], v[4:5]
	v_pk_mul_f32 v[4:5], v[190:191], v[146:147]
	v_pk_mul_f32 v[2:3], v[2:3], v[8:9]
	v_mul_f32_e32 v7, 0xbfb8aa3b, v4
	v_exp_f32_e32 v7, v7
	v_cvt_pk_bf16_f32 v2, v2, v3
	v_add_f32_e32 v7, 1.0, v7
	v_rcp_f32_e32 v8, v7
	v_mul_f32_e32 v7, 0xbfb8aa3b, v5
	v_exp_f32_e32 v7, v7
	s_nop 0
	v_add_f32_e32 v7, 1.0, v7
	v_rcp_f32_e32 v9, v7
	s_nop 0
	v_pk_mul_f32 v[4:5], v[4:5], v[8:9]
	v_pk_mul_f32 v[8:9], v[190:191], v[152:153]
	v_pk_mul_f32 v[4:5], v[4:5], v[10:11]
	v_mul_f32_e32 v7, 0xbfb8aa3b, v8
	v_exp_f32_e32 v7, v7
	v_cvt_pk_bf16_f32 v4, v4, v5
	v_add_f32_e32 v7, 1.0, v7
	v_rcp_f32_e32 v10, v7
	v_mul_f32_e32 v7, 0xbfb8aa3b, v9
	v_exp_f32_e32 v7, v7
	s_nop 0
	v_add_f32_e32 v7, 1.0, v7
	v_rcp_f32_e32 v11, v7
	s_nop 0
	v_pk_mul_f32 v[8:9], v[8:9], v[10:11]
	v_pk_mul_f32 v[10:11], v[190:191], v[148:149]
	v_pk_mul_f32 v[8:9], v[8:9], v[12:13]
	v_mul_f32_e32 v7, 0xbfb8aa3b, v10
	v_exp_f32_e32 v7, v7
	v_cvt_pk_bf16_f32 v3, v8, v9
	v_mov_b64_e32 v[8:9], s[14:15]
	v_mad_i64_i32 v[8:9], s[6:7], v6, s40, v[8:9]
	v_add_f32_e32 v7, 1.0, v7
	v_rcp_f32_e32 v12, v7
	v_mul_f32_e32 v7, 0xbfb8aa3b, v11
	v_exp_f32_e32 v7, v7
	v_lshl_add_u64 v[8:9], s[86:87], 1, v[8:9]
	v_lshl_add_u64 v[8:9], v[8:9], 0, v[172:173]
	s_mov_b64 s[6:7], 0
	v_add_f32_e32 v7, 1.0, v7
	v_rcp_f32_e32 v13, v7
	s_nop 0
	v_pk_mul_f32 v[10:11], v[10:11], v[12:13]
	s_nop 0
	v_pk_mul_f32 v[10:11], v[10:11], v[14:15]
	s_nop 0
	v_cvt_pk_bf16_f32 v5, v10, v11
	global_store_dwordx4 v[8:9], v[2:5], off sc0 sc1

; __device__ __forceinline__ unsigned cvt_pk_bf16(float lo, float hi) { const f32x2_t v = {lo, hi}; return __builtin_bit_cast(unsigned, __builtin_convertvector(v, bf16x2_t)); }
;     __device__ __forceinline__ void operator()(const f32x4 (&acc)[2][2][4][2], const Unit& u, int wr, int wc, int fr, int fq) const {
;     ...
;                         u32x4 w; w.x = cvt_pk_bf16(v0[0], v0[1]); w.y = cvt_pk_bf16(v0[2], v0[3]); w.z = cvt_pk_bf16(v1[0], v1[1]); w.w = cvt_pk_bf16(v1[2], v1[3]);
;                         if (type == 1) *(u32x4*)(P + (size_t)row * 5120 + 1024 + (pnl - 8) * BM + bj * HALF + lc) = w;
;                         else { const int cg = (pnl - (type == 3 ? 12 : 16)) * BM + bj * HALF + lc;
;                             *(u32x4*)((type == 3 ? XB : ZB) + ((size_t)(cg >> 4) * 8448 + row) * 16 + (cg & 8)) = w; } }
.LBB0_675:
	v_ashrrev_i32_e32 v7, 31, v6
	v_cvt_pk_bf16_f32 v2, v2, v3
	v_cvt_pk_bf16_f32 v3, v4, v5
	v_cvt_pk_bf16_f32 v4, v12, v13
	v_cvt_pk_bf16_f32 v5, v10, v11
	s_mov_b64 s[88:89], -1
	s_and_b64 vcc, exec, s[84:85]
	s_cbranch_vccz .LBB0_677
	v_ashrrev_i32_e32 v10, 4, v18
	s_and_b64 s[44:45], s[78:79], exec
	v_mad_i64_i32 v[10:11], s[88:89], v10, s41, v[6:7]
	s_cselect_b32 s45, s29, s53
	s_cselect_b32 s44, s28, s52
	v_lshlrev_b64 v[10:11], 5, v[10:11]
	v_lshl_add_u64 v[10:11], s[44:45], 0, v[10:11]
	v_lshlrev_b32_e32 v12, 1, v174
	v_mov_b32_e32 v13, v173
	v_lshl_add_u64 v[10:11], v[10:11], 0, v[12:13]
	global_store_dwordx4 v[10:11], v[2:5], off sc0 sc1
	s_mov_b64 s[88:89], 0
.LBB0_677:
	v_mad_i64_i32 v[10:11], s[44:45], v6, s40, 0
	s_andn2_b64 vcc, exec, s[88:89]
	v_lshl_add_u64 v[10:11], s[14:15], 0, v[10:11]
	s_cbranch_vccnz .LBB0_679
	s_lshl_b32 s34, s67, 1
	v_lshl_add_u64 v[12:13], v[10:11], 0, s[34:35]
	v_lshl_add_u64 v[12:13], v[12:13], 0, v[172:173]
	global_store_dwordx4 v[12:13], v[2:5], off offset:-2048 sc0 sc1

; __device__ __forceinline__ unsigned cvt_pk_bf16(float lo, float hi) { const f32x2_t v = {lo, hi}; return __builtin_bit_cast(unsigned, __builtin_convertvector(v, bf16x2_t)); }
;     __device__ __forceinline__ void operator()(const f32x4 (&acc)[2][2][4][2], const Unit& u, int wr, int wc, int fr, int fq) const {
;     ...
;                         u32x4 w; w.x = cvt_pk_bf16(v0[0], v0[1]); w.y = cvt_pk_bf16(v0[2], v0[3]); w.z = cvt_pk_bf16(v1[0], v1[1]); w.w = cvt_pk_bf16(v1[2], v1[3]);
;                         if (type == 1) *(u32x4*)(P + (size_t)row * 5120 + 1024 + (pnl - 8) * BM + bj * HALF + lc) = w;
;                         else { const int cg = (pnl - (type == 3 ? 12 : 16)) * BM + bj * HALF + lc;
;                             *(u32x4*)((type == 3 ? XB : ZB) + ((size_t)(cg >> 4) * 8448 + row) * 16 + (cg & 8)) = w; } }
.LBB0_683:
	v_cvt_pk_bf16_f32 v2, v2, v3
	v_cvt_pk_bf16_f32 v3, v4, v5
	v_cvt_pk_bf16_f32 v4, v14, v15
	v_cvt_pk_bf16_f32 v5, v12, v13
	s_and_b64 vcc, exec, s[6:7]
	s_mov_b64 s[6:7], -1
	s_cbranch_vccnz .LBB0_688
	v_ashrrev_i32_e32 v12, 4, v18
	v_or_b32_e32 v12, 8, v12
	s_and_b64 s[6:7], s[78:79], exec
	v_mad_i64_i32 v[12:13], s[44:45], v12, s41, v[6:7]
	s_cselect_b32 s7, s29, s53
	s_cselect_b32 s6, s28, s52
	v_lshlrev_b64 v[12:13], 5, v[12:13]
	v_lshl_add_u64 v[12:13], s[6:7], 0, v[12:13]
	v_lshlrev_b32_e32 v14, 1, v174
	v_mov_b32_e32 v15, v173
	v_lshl_add_u64 v[12:13], v[12:13], 0, v[14:15]
	global_store_dwordx4 v[12:13], v[2:5], off sc0 sc1
	s_cbranch_execz .LBB0_689

; __device__ __forceinline__ unsigned cvt_pk_bf16(float lo, float hi) { const f32x2_t v = {lo, hi}; return __builtin_bit_cast(unsigned, __builtin_convertvector(v, bf16x2_t)); }
;     __device__ __forceinline__ void operator()(const f32x4 (&acc)[2][2][4][2], const Unit& u, int wr, int wc, int fr, int fq) const {
;     ...
;                         u32x4 w; w.x = cvt_pk_bf16(v0[0], v0[1]); w.y = cvt_pk_bf16(v0[2], v0[3]); w.z = cvt_pk_bf16(v1[0], v1[1]); w.w = cvt_pk_bf16(v1[2], v1[3]);
;                         if (type == 1) *(u32x4*)(P + (size_t)row * 5120 + 1024 + (pnl - 8) * BM + bj * HALF + lc) = w;
.LBB0_689:
	s_lshl_b32 s34, s67, 1
	v_lshl_add_u64 v[10:11], v[10:11], 0, s[34:35]
	v_lshl_add_u64 v[10:11], v[10:11], 0, v[172:173]
	global_store_dwordx4 v[10:11], v[2:5], off offset:-1792 sc0 sc1
	s_andn2_b64 vcc, exec, s[76:77]
	s_cbranch_vccnz .LBB0_693

; __device__ __forceinline__ unsigned cvt_pk_bf16(float lo, float hi) { const f32x2_t v = {lo, hi}; return __builtin_bit_cast(unsigned, __builtin_convertvector(v, bf16x2_t)); }
; __device__ __forceinline__ float silu_f(float x) { return x * __builtin_amdgcn_rcpf(1.0f + __expf(-x)); }
;     __device__ __forceinline__ void operator()(const f32x4 (&acc)[2][2][4][2], const Unit& u, int wr, int wc, int fr, int fq) const {
;     ...
;             for (int m = 0; m < 4; ++m) { const int row = row0 + ai * HALF + m * 16;
;                 if (type == 0) { f32x4 p0, p1;
; #pragma unroll
;                     for (int j = 0; j < 4; ++j) { p0[j] = (acc[ai][0][m][0][j] * osc) * silu_f(acc[ai][1][m][0][j] * osc); p1[j] = (acc[ai][0][m][1][j] * osc) * silu_f(acc[ai][1][m][1][j] * osc); }
;                     u32x4 w; w.x = cvt_pk_bf16(p0[0], p0[1]); w.y = cvt_pk_bf16(p0[2], p0[3]); w.z = cvt_pk_bf16(p1[0], p1[1]); w.w = cvt_pk_bf16(p1[2], p1[3]);
;                     *(u32x4*)(P + (size_t)row * 5120 + pnl * HALF + lc) = w; }
.LBB0_693:
	v_cndmask_b32_e64 v2, 0, 1, s[8:9]
	v_or_b32_e32 v8, 16, v6
	v_cmp_ne_u32_e64 s[6:7], 1, v2
	s_andn2_b64 vcc, exec, s[8:9]
	s_mov_b64 s[8:9], -1
	s_cbranch_vccnz .LBB0_695
	s_waitcnt lgkmcnt(0)
	v_pk_mul_f32 v[2:3], v[190:191], v[134:135]
	v_pk_mul_f32 v[10:11], v[190:191], v[142:143]
	v_mul_f32_e32 v4, 0xbfb8aa3b, v2
	v_mul_f32_e32 v5, 0xbfb8aa3b, v3
	v_exp_f32_e32 v4, v4
	v_exp_f32_e32 v5, v5
	v_pk_mul_f32 v[12:13], v[190:191], v[138:139]
	v_pk_mul_f32 v[14:15], v[190:191], v[144:145]
	v_add_f32_e32 v4, 1.0, v4
	v_add_f32_e32 v5, 1.0, v5
	v_rcp_f32_e32 v4, v4
	v_rcp_f32_e32 v5, v5
	v_pk_mul_f32 v[16:17], v[190:191], v[140:141]
	v_pk_mul_f32 v[2:3], v[2:3], v[4:5]
	v_pk_mul_f32 v[4:5], v[190:191], v[130:131]
	v_pk_mul_f32 v[2:3], v[2:3], v[10:11]
	v_mul_f32_e32 v7, 0xbfb8aa3b, v4
	v_exp_f32_e32 v7, v7
	v_cvt_pk_bf16_f32 v2, v2, v3
	v_add_f32_e32 v7, 1.0, v7
	v_rcp_f32_e32 v10, v7
	v_mul_f32_e32 v7, 0xbfb8aa3b, v5
	v_exp_f32_e32 v7, v7
	s_nop 0
	v_add_f32_e32 v7, 1.0, v7
	v_rcp_f32_e32 v11, v7
	s_nop 0
	v_pk_mul_f32 v[4:5], v[4:5], v[10:11]
	v_pk_mul_f32 v[10:11], v[190:191], v[136:137]
	v_pk_mul_f32 v[4:5], v[4:5], v[12:13]
	v_mul_f32_e32 v7, 0xbfb8aa3b, v10
	v_exp_f32_e32 v7, v7
	v_cvt_pk_bf16_f32 v4, v4, v5
	v_add_f32_e32 v7, 1.0, v7
	v_rcp_f32_e32 v12, v7
	v_mul_f32_e32 v7, 0xbfb8aa3b, v11
	v_exp_f32_e32 v7, v7
	s_nop 0
	v_add_f32_e32 v7, 1.0, v7
	v_rcp_f32_e32 v13, v7
	s_nop 0
	v_pk_mul_f32 v[10:11], v[10:11], v[12:13]
	v_pk_mul_f32 v[12:13], v[190:191], v[132:133]
	v_pk_mul_f32 v[10:11], v[10:11], v[14:15]
	v_mul_f32_e32 v7, 0xbfb8aa3b, v12
	v_exp_f32_e32 v7, v7
	v_cvt_pk_bf16_f32 v3, v10, v11
	v_mov_b64_e32 v[10:11], s[14:15]
	v_mad_i64_i32 v[10:11], s[8:9], v8, s40, v[10:11]
	v_add_f32_e32 v7, 1.0, v7
	v_rcp_f32_e32 v14, v7
	v_mul_f32_e32 v7, 0xbfb8aa3b, v13
	v_exp_f32_e32 v7, v7
	v_lshl_add_u64 v[10:11], s[86:87], 1, v[10:11]
	v_lshl_add_u64 v[10:11], v[10:11], 0, v[172:173]
	s_mov_b64 s[8:9], 0
	v_add_f32_e32 v7, 1.0, v7
	v_rcp_f32_e32 v15, v7
	s_nop 0
	v_pk_mul_f32 v[12:13], v[12:13], v[14:15]
	s_nop 0
	v_pk_mul_f32 v[12:13], v[12:13], v[16:17]
	s_nop 0
	v_cvt_pk_bf16_f32 v5, v12, v13
	global_store_dwordx4 v[10:11], v[2:5], off sc0 sc1

; __device__ __forceinline__ unsigned cvt_pk_bf16(float lo, float hi) { const f32x2_t v = {lo, hi}; return __builtin_bit_cast(unsigned, __builtin_convertvector(v, bf16x2_t)); }
;     __device__ __forceinline__ void operator()(const f32x4 (&acc)[2][2][4][2], const Unit& u, int wr, int wc, int fr, int fq) const {
;     ...
;                         u32x4 w; w.x = cvt_pk_bf16(v0[0], v0[1]); w.y = cvt_pk_bf16(v0[2], v0[3]); w.z = cvt_pk_bf16(v1[0], v1[1]); w.w = cvt_pk_bf16(v1[2], v1[3]);
;                         if (type == 1) *(u32x4*)(P + (size_t)row * 5120 + 1024 + (pnl - 8) * BM + bj * HALF + lc) = w;
;                         else { const int cg = (pnl - (type == 3 ? 12 : 16)) * BM + bj * HALF + lc;
;                             *(u32x4*)((type == 3 ? XB : ZB) + ((size_t)(cg >> 4) * 8448 + row) * 16 + (cg & 8)) = w; } }
.LBB0_703:
	v_ashrrev_i32_e32 v9, 31, v8
	v_cvt_pk_bf16_f32 v2, v2, v3
	v_cvt_pk_bf16_f32 v3, v4, v5
	v_cvt_pk_bf16_f32 v4, v14, v15
	v_cvt_pk_bf16_f32 v5, v12, v13
	s_and_b64 vcc, exec, s[8:9]
	s_mov_b64 s[88:89], -1
	s_cbranch_vccnz .LBB0_705
	v_ashrrev_i32_e32 v7, 4, v18
	s_and_b64 s[44:45], s[78:79], exec
	v_mad_i64_i32 v[12:13], s[88:89], v7, s41, v[8:9]
	s_cselect_b32 s45, s29, s53
	s_cselect_b32 s44, s28, s52
	v_lshlrev_b64 v[12:13], 5, v[12:13]
	v_lshl_add_u64 v[12:13], s[44:45], 0, v[12:13]
	v_lshlrev_b32_e32 v14, 1, v174
	v_mov_b32_e32 v15, v173
	v_lshl_add_u64 v[12:13], v[12:13], 0, v[14:15]
	s_mov_b64 s[88:89], 0
	global_store_dwordx4 v[12:13], v[2:5], off sc0 sc1
.LBB0_705:
	v_mad_i64_i32 v[12:13], s[44:45], v8, s40, 0
	s_andn2_b64 vcc, exec, s[88:89]
	v_lshl_add_u64 v[12:13], s[14:15], 0, v[12:13]
	s_cbranch_vccnz .LBB0_707
	s_lshl_b32 s34, s67, 1
	v_lshl_add_u64 v[14:15], v[12:13], 0, s[34:35]
	v_lshl_add_u64 v[14:15], v[14:15], 0, v[172:173]
	global_store_dwordx4 v[14:15], v[2:5], off offset:-2048 sc0 sc1

; __device__ __forceinline__ unsigned cvt_pk_bf16(float lo, float hi) { const f32x2_t v = {lo, hi}; return __builtin_bit_cast(unsigned, __builtin_convertvector(v, bf16x2_t)); }
;     __device__ __forceinline__ void operator()(const f32x4 (&acc)[2][2][4][2], const Unit& u, int wr, int wc, int fr, int fq) const {
;     ...
;                         u32x4 w; w.x = cvt_pk_bf16(v0[0], v0[1]); w.y = cvt_pk_bf16(v0[2], v0[3]); w.z = cvt_pk_bf16(v1[0], v1[1]); w.w = cvt_pk_bf16(v1[2], v1[3]);
;                         if (type == 1) *(u32x4*)(P + (size_t)row * 5120 + 1024 + (pnl - 8) * BM + bj * HALF + lc) = w;
;                         else { const int cg = (pnl - (type == 3 ? 12 : 16)) * BM + bj * HALF + lc;
;                             *(u32x4*)((type == 3 ? XB : ZB) + ((size_t)(cg >> 4) * 8448 + row) * 16 + (cg & 8)) = w; } }
.LBB0_711:
	v_cvt_pk_bf16_f32 v2, v2, v3
	v_cvt_pk_bf16_f32 v3, v4, v5
	v_cvt_pk_bf16_f32 v4, v16, v17
	v_cvt_pk_bf16_f32 v5, v14, v15
	s_and_b64 vcc, exec, s[8:9]
	s_mov_b64 s[8:9], -1
	s_cbranch_vccnz .LBB0_719
	v_ashrrev_i32_e32 v7, 4, v18
	v_or_b32_e32 v7, 8, v7
	s_and_b64 s[8:9], s[78:79], exec
	v_mad_i64_i32 v[14:15], s[44:45], v7, s41, v[8:9]
	s_cselect_b32 s9, s29, s53
	s_cselect_b32 s8, s28, s52
	v_lshlrev_b64 v[14:15], 5, v[14:15]
	v_lshl_add_u64 v[14:15], s[8:9], 0, v[14:15]
	v_lshlrev_b32_e32 v16, 1, v174
	v_mov_b32_e32 v17, v173
	v_lshl_add_u64 v[14:15], v[14:15], 0, v[16:17]
	global_store_dwordx4 v[14:15], v[2:5], off sc0 sc1
	s_cbranch_execz .LBB0_720

; __device__ __forceinline__ unsigned cvt_pk_bf16(float lo, float hi) { const f32x2_t v = {lo, hi}; return __builtin_bit_cast(unsigned, __builtin_convertvector(v, bf16x2_t)); }
;     __device__ __forceinline__ void operator()(const f32x4 (&acc)[2][2][4][2], const Unit& u, int wr, int wc, int fr, int fq) const {
;     ...
;                         u32x4 w; w.x = cvt_pk_bf16(v0[0], v0[1]); w.y = cvt_pk_bf16(v0[2], v0[3]); w.z = cvt_pk_bf16(v1[0], v1[1]); w.w = cvt_pk_bf16(v1[2], v1[3]);
;                         if (type == 1) *(u32x4*)(P + (size_t)row * 5120 + 1024 + (pnl - 8) * BM + bj * HALF + lc) = w;
.LBB0_720:
	s_lshl_b32 s34, s67, 1
	v_lshl_add_u64 v[12:13], v[12:13], 0, s[34:35]
	v_lshl_add_u64 v[12:13], v[12:13], 0, v[172:173]
	global_store_dwordx4 v[12:13], v[2:5], off offset:-1792 sc0 sc1
	s_andn2_b64 vcc, exec, s[76:77]
	s_cbranch_vccz .LBB0_714

; __device__ __forceinline__ unsigned cvt_pk_bf16(float lo, float hi) { const f32x2_t v = {lo, hi}; return __builtin_bit_cast(unsigned, __builtin_convertvector(v, bf16x2_t)); }
; __device__ __forceinline__ float silu_f(float x) { return x * __builtin_amdgcn_rcpf(1.0f + __expf(-x)); }
;     __device__ __forceinline__ void operator()(const f32x4 (&acc)[2][2][4][2], const Unit& u, int wr, int wc, int fr, int fq) const {
;     ...
;                 if (type == 0) { f32x4 p0, p1;
; #pragma unroll
;                     for (int j = 0; j < 4; ++j) { p0[j] = (acc[ai][0][m][0][j] * osc) * silu_f(acc[ai][1][m][0][j] * osc); p1[j] = (acc[ai][0][m][1][j] * osc) * silu_f(acc[ai][1][m][1][j] * osc); }
;                     u32x4 w; w.x = cvt_pk_bf16(p0[0], p0[1]); w.y = cvt_pk_bf16(p0[2], p0[3]); w.z = cvt_pk_bf16(p1[0], p1[1]); w.w = cvt_pk_bf16(p1[2], p1[3]);
;                     *(u32x4*)(P + (size_t)row * 5120 + pnl * HALF + lc) = w; }
.LBB0_722:
	s_waitcnt lgkmcnt(0)
	v_pk_mul_f32 v[2:3], v[190:191], v[118:119]
	v_pk_mul_f32 v[10:11], v[190:191], v[126:127]
	v_mul_f32_e32 v4, 0xbfb8aa3b, v2
	v_mul_f32_e32 v5, 0xbfb8aa3b, v3
	v_exp_f32_e32 v4, v4
	v_exp_f32_e32 v5, v5
	v_pk_mul_f32 v[12:13], v[190:191], v[122:123]
	v_pk_mul_f32 v[14:15], v[190:191], v[128:129]
	v_add_f32_e32 v4, 1.0, v4
	v_add_f32_e32 v5, 1.0, v5
	v_rcp_f32_e32 v4, v4
	v_rcp_f32_e32 v5, v5
	v_pk_mul_f32 v[16:17], v[190:191], v[124:125]
	v_pk_mul_f32 v[2:3], v[2:3], v[4:5]
	v_pk_mul_f32 v[4:5], v[190:191], v[114:115]
	v_pk_mul_f32 v[2:3], v[2:3], v[10:11]
	v_mul_f32_e32 v7, 0xbfb8aa3b, v4
	v_exp_f32_e32 v7, v7
	v_cvt_pk_bf16_f32 v2, v2, v3
	v_add_f32_e32 v7, 1.0, v7
	v_rcp_f32_e32 v10, v7
	v_mul_f32_e32 v7, 0xbfb8aa3b, v5
	v_exp_f32_e32 v7, v7
	s_nop 0
	v_add_f32_e32 v7, 1.0, v7
	v_rcp_f32_e32 v11, v7
	s_nop 0
	v_pk_mul_f32 v[4:5], v[4:5], v[10:11]
	v_pk_mul_f32 v[10:11], v[190:191], v[120:121]
	v_pk_mul_f32 v[4:5], v[4:5], v[12:13]
	v_mul_f32_e32 v7, 0xbfb8aa3b, v10
	v_exp_f32_e32 v7, v7
	v_cvt_pk_bf16_f32 v4, v4, v5
	v_add_f32_e32 v7, 1.0, v7
	v_rcp_f32_e32 v12, v7
	v_mul_f32_e32 v7, 0xbfb8aa3b, v11
	v_exp_f32_e32 v7, v7
	s_nop 0
	v_add_f32_e32 v7, 1.0, v7
	v_rcp_f32_e32 v13, v7
	s_nop 0
	v_pk_mul_f32 v[10:11], v[10:11], v[12:13]
	v_pk_mul_f32 v[12:13], v[190:191], v[116:117]
	v_pk_mul_f32 v[10:11], v[10:11], v[14:15]
	v_mul_f32_e32 v7, 0xbfb8aa3b, v12
	v_exp_f32_e32 v7, v7
	v_cvt_pk_bf16_f32 v3, v10, v11
	v_mov_b64_e32 v[10:11], s[14:15]
	v_mad_i64_i32 v[10:11], s[8:9], v8, s40, v[10:11]
	v_add_f32_e32 v7, 1.0, v7
	v_rcp_f32_e32 v14, v7
	v_mul_f32_e32 v7, 0xbfb8aa3b, v13
	v_exp_f32_e32 v7, v7
	v_lshl_add_u64 v[10:11], s[86:87], 1, v[10:11]
	v_lshl_add_u64 v[10:11], v[10:11], 0, v[172:173]
	s_mov_b64 s[8:9], 0
	v_add_f32_e32 v7, 1.0, v7
	v_rcp_f32_e32 v15, v7
	s_nop 0
	v_pk_mul_f32 v[12:13], v[12:13], v[14:15]
	s_nop 0
	v_pk_mul_f32 v[12:13], v[12:13], v[16:17]
	s_nop 0
	v_cvt_pk_bf16_f32 v5, v12, v13
	global_store_dwordx4 v[10:11], v[2:5], off sc0 sc1

; __device__ __forceinline__ unsigned cvt_pk_bf16(float lo, float hi) { const f32x2_t v = {lo, hi}; return __builtin_bit_cast(unsigned, __builtin_convertvector(v, bf16x2_t)); }
; __device__ __forceinline__ float silu_f(float x) { return x * __builtin_amdgcn_rcpf(1.0f + __expf(-x)); }
;     __device__ __forceinline__ void operator()(const f32x4 (&acc)[2][2][4][2], const Unit& u, int wr, int wc, int fr, int fq) const {
;     ...
;                 if (type == 0) { f32x4 p0, p1;
; #pragma unroll
;                     for (int j = 0; j < 4; ++j) { p0[j] = (acc[ai][0][m][0][j] * osc) * silu_f(acc[ai][1][m][0][j] * osc); p1[j] = (acc[ai][0][m][1][j] * osc) * silu_f(acc[ai][1][m][1][j] * osc); }
;                     u32x4 w; w.x = cvt_pk_bf16(p0[0], p0[1]); w.y = cvt_pk_bf16(p0[2], p0[3]); w.z = cvt_pk_bf16(p1[0], p1[1]); w.w = cvt_pk_bf16(p1[2], p1[3]);
;                     *(u32x4*)(P + (size_t)row * 5120 + pnl * HALF + lc) = w; }
.LBB0_750:
	s_waitcnt lgkmcnt(0)
	v_pk_mul_f32 v[2:3], v[190:191], v[102:103]
	v_pk_mul_f32 v[10:11], v[190:191], v[110:111]
	v_mul_f32_e32 v4, 0xbfb8aa3b, v2
	v_mul_f32_e32 v5, 0xbfb8aa3b, v3
	v_exp_f32_e32 v4, v4
	v_exp_f32_e32 v5, v5
	v_pk_mul_f32 v[12:13], v[190:191], v[106:107]
	v_pk_mul_f32 v[14:15], v[190:191], v[112:113]
	v_add_f32_e32 v4, 1.0, v4
	v_add_f32_e32 v5, 1.0, v5
	v_rcp_f32_e32 v4, v4
	v_rcp_f32_e32 v5, v5
	v_pk_mul_f32 v[16:17], v[190:191], v[108:109]
	v_pk_mul_f32 v[2:3], v[2:3], v[4:5]
	v_pk_mul_f32 v[4:5], v[190:191], v[98:99]
	v_pk_mul_f32 v[2:3], v[2:3], v[10:11]
	v_mul_f32_e32 v7, 0xbfb8aa3b, v4
	v_exp_f32_e32 v7, v7
	v_cvt_pk_bf16_f32 v2, v2, v3
	v_add_f32_e32 v7, 1.0, v7
	v_rcp_f32_e32 v10, v7
	v_mul_f32_e32 v7, 0xbfb8aa3b, v5
	v_exp_f32_e32 v7, v7
	s_nop 0
	v_add_f32_e32 v7, 1.0, v7
	v_rcp_f32_e32 v11, v7
	s_nop 0
	v_pk_mul_f32 v[4:5], v[4:5], v[10:11]
	v_pk_mul_f32 v[10:11], v[190:191], v[104:105]
	v_pk_mul_f32 v[4:5], v[4:5], v[12:13]
	v_mul_f32_e32 v7, 0xbfb8aa3b, v10
	v_exp_f32_e32 v7, v7
	v_cvt_pk_bf16_f32 v4, v4, v5
	v_add_f32_e32 v7, 1.0, v7
	v_rcp_f32_e32 v12, v7
	v_mul_f32_e32 v7, 0xbfb8aa3b, v11
	v_exp_f32_e32 v7, v7
	s_nop 0
	v_add_f32_e32 v7, 1.0, v7
	v_rcp_f32_e32 v13, v7
	s_nop 0
	v_pk_mul_f32 v[10:11], v[10:11], v[12:13]
	v_pk_mul_f32 v[12:13], v[190:191], v[100:101]
	v_pk_mul_f32 v[10:11], v[10:11], v[14:15]
	v_mul_f32_e32 v7, 0xbfb8aa3b, v12
	v_exp_f32_e32 v7, v7
	v_cvt_pk_bf16_f32 v3, v10, v11
	v_mov_b64_e32 v[10:11], s[14:15]
	v_mad_i64_i32 v[10:11], s[8:9], v8, s40, v[10:11]
	v_add_f32_e32 v7, 1.0, v7
	v_rcp_f32_e32 v14, v7
	v_mul_f32_e32 v7, 0xbfb8aa3b, v13
	v_exp_f32_e32 v7, v7
	v_lshl_add_u64 v[10:11], s[86:87], 1, v[10:11]
	v_lshl_add_u64 v[10:11], v[10:11], 0, v[172:173]
	s_mov_b64 s[8:9], 0
	v_add_f32_e32 v7, 1.0, v7
	v_rcp_f32_e32 v15, v7
	s_nop 0
	v_pk_mul_f32 v[12:13], v[12:13], v[14:15]
	s_nop 0
	v_pk_mul_f32 v[12:13], v[12:13], v[16:17]
	s_nop 0
	v_cvt_pk_bf16_f32 v5, v12, v13
	global_store_dwordx4 v[10:11], v[2:5], off sc0 sc1

; __device__ __forceinline__ unsigned cvt_pk_bf16(float lo, float hi) { const f32x2_t v = {lo, hi}; return __builtin_bit_cast(unsigned, __builtin_convertvector(v, bf16x2_t)); }
; __device__ __forceinline__ float silu_f(float x) { return x * __builtin_amdgcn_rcpf(1.0f + __expf(-x)); }
;     __device__ __forceinline__ void operator()(const f32x4 (&acc)[2][2][4][2], const Unit& u, int wr, int wc, int fr, int fq) const {
;     ...
;                 if (type == 0) { f32x4 p0, p1;
; #pragma unroll
;                     for (int j = 0; j < 4; ++j) { p0[j] = (acc[ai][0][m][0][j] * osc) * silu_f(acc[ai][1][m][0][j] * osc); p1[j] = (acc[ai][0][m][1][j] * osc) * silu_f(acc[ai][1][m][1][j] * osc); }
;                     u32x4 w; w.x = cvt_pk_bf16(p0[0], p0[1]); w.y = cvt_pk_bf16(p0[2], p0[3]); w.z = cvt_pk_bf16(p1[0], p1[1]); w.w = cvt_pk_bf16(p1[2], p1[3]);
;                     *(u32x4*)(P + (size_t)row * 5120 + pnl * HALF + lc) = w; }
.LBB0_778:
	s_waitcnt lgkmcnt(0)
	v_pk_mul_f32 v[2:3], v[190:191], v[86:87]
	v_pk_mul_f32 v[10:11], v[190:191], v[94:95]
	v_mul_f32_e32 v4, 0xbfb8aa3b, v2
	v_mul_f32_e32 v5, 0xbfb8aa3b, v3
	v_exp_f32_e32 v4, v4
	v_exp_f32_e32 v5, v5
	v_pk_mul_f32 v[12:13], v[190:191], v[90:91]
	v_pk_mul_f32 v[14:15], v[190:191], v[96:97]
	v_add_f32_e32 v4, 1.0, v4
	v_add_f32_e32 v5, 1.0, v5
	v_rcp_f32_e32 v4, v4
	v_rcp_f32_e32 v5, v5
	v_pk_mul_f32 v[16:17], v[190:191], v[92:93]
	v_pk_mul_f32 v[2:3], v[2:3], v[4:5]
	v_pk_mul_f32 v[4:5], v[190:191], v[82:83]
	v_pk_mul_f32 v[2:3], v[2:3], v[10:11]
	v_mul_f32_e32 v7, 0xbfb8aa3b, v4
	v_exp_f32_e32 v7, v7
	v_cvt_pk_bf16_f32 v2, v2, v3
	v_add_f32_e32 v7, 1.0, v7
	v_rcp_f32_e32 v10, v7
	v_mul_f32_e32 v7, 0xbfb8aa3b, v5
	v_exp_f32_e32 v7, v7
	s_nop 0
	v_add_f32_e32 v7, 1.0, v7
	v_rcp_f32_e32 v11, v7
	s_nop 0
	v_pk_mul_f32 v[4:5], v[4:5], v[10:11]
	v_pk_mul_f32 v[10:11], v[190:191], v[88:89]
	v_pk_mul_f32 v[4:5], v[4:5], v[12:13]
	v_mul_f32_e32 v7, 0xbfb8aa3b, v10
	v_exp_f32_e32 v7, v7
	v_cvt_pk_bf16_f32 v4, v4, v5
	v_add_f32_e32 v7, 1.0, v7
	v_rcp_f32_e32 v12, v7
	v_mul_f32_e32 v7, 0xbfb8aa3b, v11
	v_exp_f32_e32 v7, v7
	s_nop 0
	v_add_f32_e32 v7, 1.0, v7
	v_rcp_f32_e32 v13, v7
	s_nop 0
	v_pk_mul_f32 v[10:11], v[10:11], v[12:13]
	v_pk_mul_f32 v[12:13], v[190:191], v[84:85]
	v_pk_mul_f32 v[10:11], v[10:11], v[14:15]
	v_mul_f32_e32 v7, 0xbfb8aa3b, v12
	v_exp_f32_e32 v7, v7
	v_cvt_pk_bf16_f32 v3, v10, v11
	v_mov_b64_e32 v[10:11], s[14:15]
	v_mad_i64_i32 v[10:11], s[8:9], v8, s40, v[10:11]
	v_add_f32_e32 v7, 1.0, v7
	v_rcp_f32_e32 v14, v7
	v_mul_f32_e32 v7, 0xbfb8aa3b, v13
	v_exp_f32_e32 v7, v7
	v_lshl_add_u64 v[10:11], s[86:87], 1, v[10:11]
	v_lshl_add_u64 v[10:11], v[10:11], 0, v[172:173]
	s_mov_b64 s[8:9], 0
	v_add_f32_e32 v7, 1.0, v7
	v_rcp_f32_e32 v15, v7
	s_nop 0
	v_pk_mul_f32 v[12:13], v[12:13], v[14:15]
	s_nop 0
	v_pk_mul_f32 v[12:13], v[12:13], v[16:17]
	s_nop 0
	v_cvt_pk_bf16_f32 v5, v12, v13
	global_store_dwordx4 v[10:11], v[2:5], off sc0 sc1

; __device__ __forceinline__ unsigned cvt_pk_bf16(float lo, float hi) { const f32x2_t v = {lo, hi}; return __builtin_bit_cast(unsigned, __builtin_convertvector(v, bf16x2_t)); }
; __device__ __forceinline__ float silu_f(float x) { return x * __builtin_amdgcn_rcpf(1.0f + __expf(-x)); }
;     __device__ __forceinline__ void operator()(const f32x4 (&acc)[2][2][4][2], const Unit& u, int wr, int wc, int fr, int fq) const {
;     ...
;                 if (type == 0) { f32x4 p0, p1;
; #pragma unroll
;                     for (int j = 0; j < 4; ++j) { p0[j] = (acc[ai][0][m][0][j] * osc) * silu_f(acc[ai][1][m][0][j] * osc); p1[j] = (acc[ai][0][m][1][j] * osc) * silu_f(acc[ai][1][m][1][j] * osc); }
;                     u32x4 w; w.x = cvt_pk_bf16(p0[0], p0[1]); w.y = cvt_pk_bf16(p0[2], p0[3]); w.z = cvt_pk_bf16(p1[0], p1[1]); w.w = cvt_pk_bf16(p1[2], p1[3]);
;                     *(u32x4*)(P + (size_t)row * 5120 + pnl * HALF + lc) = w; }
.LBB0_806:
	s_waitcnt lgkmcnt(0)
	v_pk_mul_f32 v[2:3], v[190:191], v[70:71]
	v_pk_mul_f32 v[10:11], v[190:191], v[78:79]
	v_mul_f32_e32 v4, 0xbfb8aa3b, v2
	v_mul_f32_e32 v5, 0xbfb8aa3b, v3
	v_exp_f32_e32 v4, v4
	v_exp_f32_e32 v5, v5
	v_pk_mul_f32 v[12:13], v[190:191], v[74:75]
	v_pk_mul_f32 v[14:15], v[190:191], v[80:81]
	v_add_f32_e32 v4, 1.0, v4
	v_add_f32_e32 v5, 1.0, v5
	v_rcp_f32_e32 v4, v4
	v_rcp_f32_e32 v5, v5
	v_pk_mul_f32 v[16:17], v[190:191], v[76:77]
	v_pk_mul_f32 v[2:3], v[2:3], v[4:5]
	v_pk_mul_f32 v[4:5], v[190:191], v[66:67]
	v_pk_mul_f32 v[2:3], v[2:3], v[10:11]
	v_mul_f32_e32 v7, 0xbfb8aa3b, v4
	v_exp_f32_e32 v7, v7
	v_cvt_pk_bf16_f32 v2, v2, v3
	v_add_f32_e32 v7, 1.0, v7
	v_rcp_f32_e32 v10, v7
	v_mul_f32_e32 v7, 0xbfb8aa3b, v5
	v_exp_f32_e32 v7, v7
	s_nop 0
	v_add_f32_e32 v7, 1.0, v7
	v_rcp_f32_e32 v11, v7
	s_nop 0
	v_pk_mul_f32 v[4:5], v[4:5], v[10:11]
	v_pk_mul_f32 v[10:11], v[190:191], v[72:73]
	v_pk_mul_f32 v[4:5], v[4:5], v[12:13]
	v_mul_f32_e32 v7, 0xbfb8aa3b, v10
	v_exp_f32_e32 v7, v7
	v_cvt_pk_bf16_f32 v4, v4, v5
	v_add_f32_e32 v7, 1.0, v7
	v_rcp_f32_e32 v12, v7
	v_mul_f32_e32 v7, 0xbfb8aa3b, v11
	v_exp_f32_e32 v7, v7
	s_nop 0
	v_add_f32_e32 v7, 1.0, v7
	v_rcp_f32_e32 v13, v7
	s_nop 0
	v_pk_mul_f32 v[10:11], v[10:11], v[12:13]
	v_pk_mul_f32 v[12:13], v[190:191], v[68:69]
	v_pk_mul_f32 v[10:11], v[10:11], v[14:15]
	v_mul_f32_e32 v7, 0xbfb8aa3b, v12
	v_exp_f32_e32 v7, v7
	v_cvt_pk_bf16_f32 v3, v10, v11
	v_mov_b64_e32 v[10:11], s[14:15]
	v_mad_i64_i32 v[10:11], s[8:9], v8, s40, v[10:11]
	v_add_f32_e32 v7, 1.0, v7
	v_rcp_f32_e32 v14, v7
	v_mul_f32_e32 v7, 0xbfb8aa3b, v13
	v_exp_f32_e32 v7, v7
	v_lshl_add_u64 v[10:11], s[86:87], 1, v[10:11]
	v_lshl_add_u64 v[10:11], v[10:11], 0, v[172:173]
	s_mov_b64 s[8:9], 0
	v_add_f32_e32 v7, 1.0, v7
	v_rcp_f32_e32 v15, v7
	s_nop 0
	v_pk_mul_f32 v[12:13], v[12:13], v[14:15]
	s_nop 0
	v_pk_mul_f32 v[12:13], v[12:13], v[16:17]
	s_nop 0
	v_cvt_pk_bf16_f32 v5, v12, v13
	global_store_dwordx4 v[10:11], v[2:5], off sc0 sc1

; __device__ __forceinline__ unsigned cvt_pk_bf16(float lo, float hi) { const f32x2_t v = {lo, hi}; return __builtin_bit_cast(unsigned, __builtin_convertvector(v, bf16x2_t)); }
; __device__ __forceinline__ float silu_f(float x) { return x * __builtin_amdgcn_rcpf(1.0f + __expf(-x)); }
;     __device__ __forceinline__ void operator()(const f32x4 (&acc)[2][2][4][2], const Unit& u, int wr, int wc, int fr, int fq) const {
;     ...
;                 if (type == 0) { f32x4 p0, p1;
; #pragma unroll
;                     for (int j = 0; j < 4; ++j) { p0[j] = (acc[ai][0][m][0][j] * osc) * silu_f(acc[ai][1][m][0][j] * osc); p1[j] = (acc[ai][0][m][1][j] * osc) * silu_f(acc[ai][1][m][1][j] * osc); }
;                     u32x4 w; w.x = cvt_pk_bf16(p0[0], p0[1]); w.y = cvt_pk_bf16(p0[2], p0[3]); w.z = cvt_pk_bf16(p1[0], p1[1]); w.w = cvt_pk_bf16(p1[2], p1[3]);
;                     *(u32x4*)(P + (size_t)row * 5120 + pnl * HALF + lc) = w; }
.LBB0_834:
	s_waitcnt lgkmcnt(0)
	v_pk_mul_f32 v[2:3], v[190:191], v[54:55]
	v_pk_mul_f32 v[10:11], v[190:191], v[62:63]
	v_mul_f32_e32 v4, 0xbfb8aa3b, v2
	v_mul_f32_e32 v5, 0xbfb8aa3b, v3
	v_exp_f32_e32 v4, v4
	v_exp_f32_e32 v5, v5
	v_pk_mul_f32 v[12:13], v[190:191], v[58:59]
	v_pk_mul_f32 v[14:15], v[190:191], v[64:65]
	v_add_f32_e32 v4, 1.0, v4
	v_add_f32_e32 v5, 1.0, v5
	v_rcp_f32_e32 v4, v4
	v_rcp_f32_e32 v5, v5
	v_pk_mul_f32 v[16:17], v[190:191], v[60:61]
	v_pk_mul_f32 v[2:3], v[2:3], v[4:5]
	v_pk_mul_f32 v[4:5], v[190:191], v[50:51]
	v_pk_mul_f32 v[2:3], v[2:3], v[10:11]
	v_mul_f32_e32 v7, 0xbfb8aa3b, v4
	v_exp_f32_e32 v7, v7
	v_cvt_pk_bf16_f32 v2, v2, v3
	v_add_f32_e32 v7, 1.0, v7
	v_rcp_f32_e32 v10, v7
	v_mul_f32_e32 v7, 0xbfb8aa3b, v5
	v_exp_f32_e32 v7, v7
	s_nop 0
	v_add_f32_e32 v7, 1.0, v7
	v_rcp_f32_e32 v11, v7
	s_nop 0
	v_pk_mul_f32 v[4:5], v[4:5], v[10:11]
	v_pk_mul_f32 v[10:11], v[190:191], v[56:57]
	v_pk_mul_f32 v[4:5], v[4:5], v[12:13]
	v_mul_f32_e32 v7, 0xbfb8aa3b, v10
	v_exp_f32_e32 v7, v7
	v_cvt_pk_bf16_f32 v4, v4, v5
	v_add_f32_e32 v7, 1.0, v7
	v_rcp_f32_e32 v12, v7
	v_mul_f32_e32 v7, 0xbfb8aa3b, v11
	v_exp_f32_e32 v7, v7
	s_nop 0
	v_add_f32_e32 v7, 1.0, v7
	v_rcp_f32_e32 v13, v7
	s_nop 0
	v_pk_mul_f32 v[10:11], v[10:11], v[12:13]
	v_pk_mul_f32 v[12:13], v[190:191], v[52:53]
	v_pk_mul_f32 v[10:11], v[10:11], v[14:15]
	v_mul_f32_e32 v7, 0xbfb8aa3b, v12
	v_exp_f32_e32 v7, v7
	v_cvt_pk_bf16_f32 v3, v10, v11
	v_mov_b64_e32 v[10:11], s[14:15]
	v_mad_i64_i32 v[10:11], s[8:9], v8, s40, v[10:11]
	v_add_f32_e32 v7, 1.0, v7
	v_rcp_f32_e32 v14, v7
	v_mul_f32_e32 v7, 0xbfb8aa3b, v13
	v_exp_f32_e32 v7, v7
	v_lshl_add_u64 v[10:11], s[86:87], 1, v[10:11]
	v_lshl_add_u64 v[10:11], v[10:11], 0, v[172:173]
	s_mov_b64 s[8:9], 0
	v_add_f32_e32 v7, 1.0, v7
	v_rcp_f32_e32 v15, v7
	s_nop 0
	v_pk_mul_f32 v[12:13], v[12:13], v[14:15]
	s_nop 0
	v_pk_mul_f32 v[12:13], v[12:13], v[16:17]
	s_nop 0
	v_cvt_pk_bf16_f32 v5, v12, v13
	global_store_dwordx4 v[10:11], v[2:5], off sc0 sc1

; __device__ __forceinline__ unsigned cvt_pk_bf16(float lo, float hi) { const f32x2_t v = {lo, hi}; return __builtin_bit_cast(unsigned, __builtin_convertvector(v, bf16x2_t)); }
; __device__ __forceinline__ float silu_f(float x) { return x * __builtin_amdgcn_rcpf(1.0f + __expf(-x)); }
;     __device__ __forceinline__ void operator()(const f32x4 (&acc)[2][2][4][2], const Unit& u, int wr, int wc, int fr, int fq) const {
;     ...
;                 if (type == 0) { f32x4 p0, p1;
; #pragma unroll
;                     for (int j = 0; j < 4; ++j) { p0[j] = (acc[ai][0][m][0][j] * osc) * silu_f(acc[ai][1][m][0][j] * osc); p1[j] = (acc[ai][0][m][1][j] * osc) * silu_f(acc[ai][1][m][1][j] * osc); }
;                     u32x4 w; w.x = cvt_pk_bf16(p0[0], p0[1]); w.y = cvt_pk_bf16(p0[2], p0[3]); w.z = cvt_pk_bf16(p1[0], p1[1]); w.w = cvt_pk_bf16(p1[2], p1[3]);
;                     *(u32x4*)(P + (size_t)row * 5120 + pnl * HALF + lc) = w; }
.LBB0_862:
	s_waitcnt lgkmcnt(0)
	v_pk_mul_f32 v[2:3], v[190:191], v[38:39]
	v_pk_mul_f32 v[8:9], v[190:191], v[46:47]
	v_mul_f32_e32 v4, 0xbfb8aa3b, v2
	v_mul_f32_e32 v5, 0xbfb8aa3b, v3
	v_exp_f32_e32 v4, v4
	v_exp_f32_e32 v5, v5
	v_pk_mul_f32 v[10:11], v[190:191], v[42:43]
	v_pk_mul_f32 v[12:13], v[190:191], v[48:49]
	v_add_f32_e32 v4, 1.0, v4
	v_add_f32_e32 v5, 1.0, v5
	v_rcp_f32_e32 v4, v4
	v_rcp_f32_e32 v5, v5
	v_pk_mul_f32 v[14:15], v[190:191], v[44:45]
	v_pk_mul_f32 v[2:3], v[2:3], v[4:5]
	v_pk_mul_f32 v[4:5], v[190:191], v[34:35]
	v_pk_mul_f32 v[2:3], v[2:3], v[8:9]
	v_mul_f32_e32 v7, 0xbfb8aa3b, v4
	v_exp_f32_e32 v7, v7
	v_cvt_pk_bf16_f32 v2, v2, v3
	v_add_f32_e32 v7, 1.0, v7
	v_rcp_f32_e32 v8, v7
	v_mul_f32_e32 v7, 0xbfb8aa3b, v5
	v_exp_f32_e32 v7, v7
	s_nop 0
	v_add_f32_e32 v7, 1.0, v7
	v_rcp_f32_e32 v9, v7
	s_nop 0
	v_pk_mul_f32 v[4:5], v[4:5], v[8:9]
	v_pk_mul_f32 v[8:9], v[190:191], v[40:41]
	v_pk_mul_f32 v[4:5], v[4:5], v[10:11]
	v_mul_f32_e32 v7, 0xbfb8aa3b, v8
	v_exp_f32_e32 v7, v7
	v_cvt_pk_bf16_f32 v4, v4, v5
	v_add_f32_e32 v7, 1.0, v7
	v_rcp_f32_e32 v10, v7
	v_mul_f32_e32 v7, 0xbfb8aa3b, v9
	v_exp_f32_e32 v7, v7
	s_nop 0
	v_add_f32_e32 v7, 1.0, v7
	v_rcp_f32_e32 v11, v7
	s_nop 0
	v_pk_mul_f32 v[8:9], v[8:9], v[10:11]
	v_pk_mul_f32 v[10:11], v[190:191], v[36:37]
	v_pk_mul_f32 v[8:9], v[8:9], v[12:13]
	v_mul_f32_e32 v7, 0xbfb8aa3b, v10
	v_exp_f32_e32 v7, v7
	v_cvt_pk_bf16_f32 v3, v8, v9
	v_mov_b64_e32 v[8:9], s[14:15]
	v_mad_i64_i32 v[8:9], s[6:7], v6, s40, v[8:9]
	v_add_f32_e32 v7, 1.0, v7
	v_rcp_f32_e32 v12, v7
	v_mul_f32_e32 v7, 0xbfb8aa3b, v11
	v_exp_f32_e32 v7, v7
	v_lshl_add_u64 v[8:9], s[86:87], 1, v[8:9]
	v_lshl_add_u64 v[8:9], v[8:9], 0, v[172:173]
	s_mov_b64 s[6:7], 0
	v_add_f32_e32 v7, 1.0, v7
	v_rcp_f32_e32 v13, v7
	s_nop 0
	v_pk_mul_f32 v[10:11], v[10:11], v[12:13]
	s_nop 0
	v_pk_mul_f32 v[10:11], v[10:11], v[14:15]
	s_nop 0
	v_cvt_pk_bf16_f32 v5, v10, v11
	global_store_dwordx4 v[8:9], v[2:5], off sc0 sc1

; __device__ __forceinline__ unsigned cvt_pk_bf16(float lo, float hi) { const f32x2_t v = {lo, hi}; return __builtin_bit_cast(unsigned, __builtin_convertvector(v, bf16x2_t)); }
;     __device__ __forceinline__ void operator()(const f32x4 (&acc)[2][2][4][2], const Unit& u, int wr, int wc, int fr, int fq) const {
;     ...
;                         u32x4 w; w.x = cvt_pk_bf16(v0[0], v0[1]); w.y = cvt_pk_bf16(v0[2], v0[3]); w.z = cvt_pk_bf16(v1[0], v1[1]); w.w = cvt_pk_bf16(v1[2], v1[3]);
;                         if (type == 1) *(u32x4*)(P + (size_t)row * 5120 + 1024 + (pnl - 8) * BM + bj * HALF + lc) = w;
;                         else { const int cg = (pnl - (type == 3 ? 12 : 16)) * BM + bj * HALF + lc;
;                             *(u32x4*)((type == 3 ? XB : ZB) + ((size_t)(cg >> 4) * 8448 + row) * 16 + (cg & 8)) = w; } }
.LBB0_871:
	v_ashrrev_i32_e32 v7, 31, v6
	v_cvt_pk_bf16_f32 v2, v2, v3
	v_cvt_pk_bf16_f32 v3, v4, v5
	v_cvt_pk_bf16_f32 v4, v12, v13
	v_cvt_pk_bf16_f32 v5, v10, v11
	s_mov_b64 s[8:9], -1
	s_and_b64 vcc, exec, s[6:7]
	v_ashrrev_i32_e32 v18, 4, v18
	v_lshlrev_b32_e32 v10, 1, v174
	s_cbranch_vccnz .LBB0_873
	s_and_b64 s[8:9], s[78:79], exec
	v_mad_i64_i32 v[12:13], s[44:45], v18, s41, v[6:7]
	s_cselect_b32 s9, s29, s53
	s_cselect_b32 s8, s28, s52
	v_lshlrev_b64 v[12:13], 5, v[12:13]
	v_lshl_add_u64 v[12:13], s[8:9], 0, v[12:13]
	v_mov_b32_e32 v11, v173
	v_lshl_add_u64 v[12:13], v[12:13], 0, v[10:11]
	s_mov_b64 s[8:9], 0
	global_store_dwordx4 v[12:13], v[2:5], off sc0 sc1
.LBB0_873:
	v_mad_i64_i32 v[12:13], s[44:45], v6, s40, 0
	s_andn2_b64 vcc, exec, s[8:9]
	v_lshl_add_u64 v[12:13], s[14:15], 0, v[12:13]
	s_cbranch_vccnz .LBB0_875
	s_lshl_b32 s34, s67, 1
	v_lshl_add_u64 v[14:15], v[12:13], 0, s[34:35]
	v_lshl_add_u64 v[14:15], v[14:15], 0, v[172:173]
	global_store_dwordx4 v[14:15], v[2:5], off offset:-2048 sc0 sc1

; __device__ __forceinline__ unsigned cvt_pk_bf16(float lo, float hi) { const f32x2_t v = {lo, hi}; return __builtin_bit_cast(unsigned, __builtin_convertvector(v, bf16x2_t)); }
;     __device__ __forceinline__ void operator()(const f32x4 (&acc)[2][2][4][2], const Unit& u, int wr, int wc, int fr, int fq) const {
;     ...
;                         u32x4 w; w.x = cvt_pk_bf16(v0[0], v0[1]); w.y = cvt_pk_bf16(v0[2], v0[3]); w.z = cvt_pk_bf16(v1[0], v1[1]); w.w = cvt_pk_bf16(v1[2], v1[3]);
;                         if (type == 1) *(u32x4*)(P + (size_t)row * 5120 + 1024 + (pnl - 8) * BM + bj * HALF + lc) = w;
;                         else { const int cg = (pnl - (type == 3 ? 12 : 16)) * BM + bj * HALF + lc;
;                             *(u32x4*)((type == 3 ? XB : ZB) + ((size_t)(cg >> 4) * 8448 + row) * 16 + (cg & 8)) = w; } }
.LBB0_879:
	v_cvt_pk_bf16_f32 v2, v2, v3
	v_cvt_pk_bf16_f32 v3, v4, v5
	v_cvt_pk_bf16_f32 v4, v16, v17
	v_cvt_pk_bf16_f32 v5, v14, v15
	s_and_b64 vcc, exec, s[6:7]
	s_mov_b64 s[4:5], -1
	s_cbranch_vccnz .LBB0_887
	v_or_b32_e32 v11, 8, v18
	s_and_b64 s[4:5], s[78:79], exec
	v_mad_i64_i32 v[14:15], s[6:7], v11, s41, v[6:7]
	s_cselect_b32 s5, s29, s53
	s_cselect_b32 s4, s28, s52
	v_lshlrev_b64 v[14:15], 5, v[14:15]
	v_lshl_add_u64 v[14:15], s[4:5], 0, v[14:15]
	v_mov_b32_e32 v11, v173
	v_lshl_add_u64 v[10:11], v[14:15], 0, v[10:11]
	global_store_dwordx4 v[10:11], v[2:5], off sc0 sc1
	s_cbranch_execz .LBB0_888

; __device__ __forceinline__ unsigned cvt_pk_bf16(float lo, float hi) { const f32x2_t v = {lo, hi}; return __builtin_bit_cast(unsigned, __builtin_convertvector(v, bf16x2_t)); }
;     __device__ __forceinline__ void operator()(const f32x4 (&acc)[2][2][4][2], const Unit& u, int wr, int wc, int fr, int fq) const {
;     ...
;                         u32x4 w; w.x = cvt_pk_bf16(v0[0], v0[1]); w.y = cvt_pk_bf16(v0[2], v0[3]); w.z = cvt_pk_bf16(v1[0], v1[1]); w.w = cvt_pk_bf16(v1[2], v1[3]);
;                         if (type == 1) *(u32x4*)(P + (size_t)row * 5120 + 1024 + (pnl - 8) * BM + bj * HALF + lc) = w;
.LBB0_888:
	s_lshl_b32 s34, s67, 1
	v_lshl_add_u64 v[10:11], v[12:13], 0, s[34:35]
	v_lshl_add_u64 v[10:11], v[10:11], 0, v[172:173]
	global_store_dwordx4 v[10:11], v[2:5], off offset:-1792 sc0 sc1
	s_andn2_b64 vcc, exec, s[76:77]
	s_cbranch_vccz .LBB0_882
